# MFMA issue order within each k-group changed to a snake so consecutive MFMAs always share one operand (power/toggle experiment), on top of the critical-path edit
# baseline (speedup 1.0000x reference)
.LBB0_306:
	ds_read_b128 v[166:169], v162
	ds_read_b128 v[170:173], v162 offset:1024
	ds_read_b128 v[174:177], v162 offset:2048
	ds_read_b128 v[180:183], v162 offset:3072
	ds_read_b128 v[184:187], v163
	ds_read_b128 v[188:191], v163 offset:1024
	ds_read_b128 v[192:195], v163 offset:2048
	ds_read_b128 v[196:199], v163 offset:3072
	s_add_u32 s30, s28, 0xfff80080
	s_addc_u32 s31, s29, -1
	s_cmp_eq_u32 s50, 28
	s_cselect_b32 s35, s3, s31
	s_cselect_b32 s34, s21, s30
	s_cselect_b32 s31, s19, s49
	s_cselect_b32 s30, s27, s48
	v_lshl_add_u64 v[160:161], s[28:29], 0, v[152:153]
	s_add_i32 m0, s33, 0xc000
	ds_read_b128 v[200:203], v164
	ds_read_b128 v[204:207], v164 offset:1024
	ds_read_b128 v[208:211], v164 offset:2048
	ds_read_b128 v[212:215], v164 offset:3072
	ds_read_b128 v[216:219], v164 offset:4096
	ds_read_b128 v[220:223], v164 offset:5120
	ds_read_b128 v[224:227], v164 offset:6144
	ds_read_b128 v[228:231], v164 offset:7168
	global_load_lds_dwordx4 v[160:161], off
	v_lshl_add_u64 v[160:161], s[28:29], 0, v[154:155]
	s_add_i32 m0, s33, 0xe000
	s_nop 0
	global_load_lds_dwordx4 v[160:161], off
	s_waitcnt vmcnt(8)
	s_waitcnt lgkmcnt(0)
	s_setprio 1
	s_barrier
	v_mfma_f32_16x16x32_bf16 v[126:129], v[166:169], v[200:203], v[126:129]
	v_mfma_f32_16x16x32_bf16 v[122:125], v[174:177], v[200:203], v[122:125]
	v_mfma_f32_16x16x32_bf16 v[106:109], v[174:177], v[208:211], v[106:109]
	v_mfma_f32_16x16x32_bf16 v[110:113], v[166:169], v[208:211], v[110:113]
	v_mfma_f32_16x16x32_bf16 v[94:97], v[166:169], v[216:219], v[94:97]
	v_mfma_f32_16x16x32_bf16 v[90:93], v[174:177], v[216:219], v[90:93]
	v_mfma_f32_16x16x32_bf16 v[74:77], v[174:177], v[224:227], v[74:77]
	v_mfma_f32_16x16x32_bf16 v[78:81], v[166:169], v[224:227], v[78:81]
	v_mfma_f32_16x16x32_bf16 v[126:129], v[170:173], v[204:207], v[126:129]
	v_mfma_f32_16x16x32_bf16 v[122:125], v[180:183], v[204:207], v[122:125]
	v_mfma_f32_16x16x32_bf16 v[106:109], v[180:183], v[212:215], v[106:109]
	v_mfma_f32_16x16x32_bf16 v[110:113], v[170:173], v[212:215], v[110:113]
	v_mfma_f32_16x16x32_bf16 v[94:97], v[170:173], v[220:223], v[94:97]
	v_mfma_f32_16x16x32_bf16 v[90:93], v[180:183], v[220:223], v[90:93]
	v_mfma_f32_16x16x32_bf16 v[74:77], v[180:183], v[228:231], v[74:77]
	v_mfma_f32_16x16x32_bf16 v[78:81], v[170:173], v[228:231], v[78:81]
	v_mfma_f32_16x16x32_bf16 v[118:121], v[184:187], v[200:203], v[118:121]
	v_mfma_f32_16x16x32_bf16 v[114:117], v[192:195], v[200:203], v[114:117]
	v_mfma_f32_16x16x32_bf16 v[98:101], v[192:195], v[208:211], v[98:101]
	v_mfma_f32_16x16x32_bf16 v[102:105], v[184:187], v[208:211], v[102:105]
	v_mfma_f32_16x16x32_bf16 v[86:89], v[184:187], v[216:219], v[86:89]
	v_mfma_f32_16x16x32_bf16 v[82:85], v[192:195], v[216:219], v[82:85]
	v_mfma_f32_16x16x32_bf16 v[66:69], v[192:195], v[224:227], v[66:69]
	v_mfma_f32_16x16x32_bf16 v[70:73], v[184:187], v[224:227], v[70:73]
	v_mfma_f32_16x16x32_bf16 v[118:121], v[188:191], v[204:207], v[118:121]
	v_mfma_f32_16x16x32_bf16 v[114:117], v[196:199], v[204:207], v[114:117]
	v_mfma_f32_16x16x32_bf16 v[98:101], v[196:199], v[212:215], v[98:101]
	v_mfma_f32_16x16x32_bf16 v[102:105], v[188:191], v[212:215], v[102:105]
	v_mfma_f32_16x16x32_bf16 v[86:89], v[188:191], v[220:223], v[86:89]
	v_mfma_f32_16x16x32_bf16 v[82:85], v[196:199], v[220:223], v[82:85]
	v_mfma_f32_16x16x32_bf16 v[66:69], v[196:199], v[228:231], v[66:69]
	v_mfma_f32_16x16x32_bf16 v[70:73], v[188:191], v[228:231], v[70:73]
	s_barrier
	s_setprio 0
	s_add_i32 s51, s45, s17
	v_lshl_add_u64 v[160:161], s[30:31], 0, v[138:139]
	s_mov_b32 m0, s51
	ds_read_b128 v[200:203], v164 offset:16384
	ds_read_b128 v[204:207], v164 offset:17408
	ds_read_b128 v[208:211], v164 offset:18432
	ds_read_b128 v[212:215], v164 offset:19456
	ds_read_b128 v[216:219], v164 offset:20480
	ds_read_b128 v[220:223], v164 offset:21504
	ds_read_b128 v[224:227], v164 offset:22528
	ds_read_b128 v[228:231], v164 offset:23552
	global_load_lds_dwordx4 v[160:161], off
	s_add_i32 m0, s51, 0x2000
	s_add_u32 s56, s30, 0x80000
	v_lshl_add_u64 v[232:233], s[30:31], 0, v[142:143]
	s_addc_u32 s57, s31, 0
	s_add_i32 s51, s47, s17
	global_load_lds_dwordx4 v[232:233], off
	v_lshl_add_u64 v[234:235], s[56:57], 0, v[138:139]
	s_mov_b32 m0, s51
	v_lshl_add_u64 v[236:237], s[34:35], 0, v[140:141]
	global_load_lds_dwordx4 v[234:235], off
	v_lshl_add_u64 v[234:235], s[56:57], 0, v[142:143]
	s_add_i32 m0, s51, 0x2000
	s_nop 0
	global_load_lds_dwordx4 v[234:235], off
	v_lshl_add_u64 v[234:235], s[34:35], 0, v[136:137]
	s_mov_b32 m0, s33
	s_nop 0
	global_load_lds_dwordx4 v[234:235], off
	s_mov_b32 m0, s36
	s_nop 0
	global_load_lds_dwordx4 v[236:237], off
	s_waitcnt vmcnt(8)
	s_waitcnt lgkmcnt(0)
	s_setprio 1
	s_barrier
	v_mfma_f32_16x16x32_bf16 v[62:65], v[166:169], v[200:203], v[62:65]
	v_mfma_f32_16x16x32_bf16 v[58:61], v[174:177], v[200:203], v[58:61]
	v_mfma_f32_16x16x32_bf16 v[42:45], v[174:177], v[208:211], v[42:45]
	v_mfma_f32_16x16x32_bf16 v[46:49], v[166:169], v[208:211], v[46:49]
	v_mfma_f32_16x16x32_bf16 v[30:33], v[166:169], v[216:219], v[30:33]
	v_mfma_f32_16x16x32_bf16 v[26:29], v[174:177], v[216:219], v[26:29]
	v_mfma_f32_16x16x32_bf16 v[10:13], v[174:177], v[224:227], v[10:13]
	v_mfma_f32_16x16x32_bf16 v[14:17], v[166:169], v[224:227], v[14:17]
	v_mfma_f32_16x16x32_bf16 v[62:65], v[170:173], v[204:207], v[62:65]
	v_mfma_f32_16x16x32_bf16 v[58:61], v[180:183], v[204:207], v[58:61]
	v_mfma_f32_16x16x32_bf16 v[42:45], v[180:183], v[212:215], v[42:45]
	v_mfma_f32_16x16x32_bf16 v[46:49], v[170:173], v[212:215], v[46:49]
	v_mfma_f32_16x16x32_bf16 v[30:33], v[170:173], v[220:223], v[30:33]
	v_mfma_f32_16x16x32_bf16 v[26:29], v[180:183], v[220:223], v[26:29]
	v_mfma_f32_16x16x32_bf16 v[10:13], v[180:183], v[228:231], v[10:13]
	v_mfma_f32_16x16x32_bf16 v[14:17], v[170:173], v[228:231], v[14:17]
	v_mfma_f32_16x16x32_bf16 v[54:57], v[184:187], v[200:203], v[54:57]
	v_mfma_f32_16x16x32_bf16 v[50:53], v[192:195], v[200:203], v[50:53]
	v_mfma_f32_16x16x32_bf16 v[34:37], v[192:195], v[208:211], v[34:37]
	v_mfma_f32_16x16x32_bf16 v[38:41], v[184:187], v[208:211], v[38:41]
	v_mfma_f32_16x16x32_bf16 v[22:25], v[184:187], v[216:219], v[22:25]
	v_mfma_f32_16x16x32_bf16 v[18:21], v[192:195], v[216:219], v[18:21]
	v_mfma_f32_16x16x32_bf16 v[2:5], v[192:195], v[224:227], v[2:5]
	v_mfma_f32_16x16x32_bf16 v[6:9], v[184:187], v[224:227], v[6:9]
	v_mfma_f32_16x16x32_bf16 v[54:57], v[188:191], v[204:207], v[54:57]
	v_mfma_f32_16x16x32_bf16 v[50:53], v[196:199], v[204:207], v[50:53]
	v_mfma_f32_16x16x32_bf16 v[34:37], v[196:199], v[212:215], v[34:37]
	v_mfma_f32_16x16x32_bf16 v[38:41], v[188:191], v[212:215], v[38:41]
	v_mfma_f32_16x16x32_bf16 v[22:25], v[188:191], v[220:223], v[22:25]
	v_mfma_f32_16x16x32_bf16 v[18:21], v[196:199], v[220:223], v[18:21]
	v_mfma_f32_16x16x32_bf16 v[2:5], v[196:199], v[228:231], v[2:5]
	v_mfma_f32_16x16x32_bf16 v[6:9], v[188:191], v[228:231], v[6:9]
	s_barrier
	s_setprio 0
	s_add_i32 s51, 0, 0x18000
	v_add_u32_e32 v144, s51, v135
	s_add_i32 s56, 0, 0x1c000
	ds_read_b128 v[166:169], v144
	ds_read_b128 v[170:173], v144 offset:1024
	ds_read_b128 v[174:177], v144 offset:2048
	ds_read_b128 v[180:183], v144 offset:3072
	v_add_u32_e32 v144, s56, v135
	ds_read_b128 v[184:187], v144
	ds_read_b128 v[188:191], v144 offset:1024
	ds_read_b128 v[192:195], v144 offset:2048
	ds_read_b128 v[196:199], v144 offset:3072
	s_add_u32 s34, s34, 0x80000
	s_addc_u32 s35, s35, 0
	s_mov_b32 m0, s37
	v_lshl_add_u64 v[238:239], s[34:35], 0, v[136:137]
	ds_read_b128 v[200:203], v164 offset:32768
	ds_read_b128 v[204:207], v164 offset:33792
	ds_read_b128 v[208:211], v164 offset:34816
	ds_read_b128 v[212:215], v164 offset:35840
	ds_read_b128 v[216:219], v164 offset:36864
	ds_read_b128 v[220:223], v164 offset:37888
	ds_read_b128 v[224:227], v164 offset:38912
	ds_read_b128 v[228:231], v164 offset:39936
	global_load_lds_dwordx4 v[238:239], off
	v_lshl_add_u64 v[238:239], s[34:35], 0, v[140:141]
	s_mov_b32 m0, s38
	s_nop 0
	global_load_lds_dwordx4 v[238:239], off
	s_waitcnt vmcnt(8)
	s_waitcnt lgkmcnt(0)
	s_setprio 1
	s_barrier
	v_mfma_f32_16x16x32_bf16 v[126:129], v[166:169], v[200:203], v[126:129]
	v_mfma_f32_16x16x32_bf16 v[122:125], v[174:177], v[200:203], v[122:125]
	v_mfma_f32_16x16x32_bf16 v[106:109], v[174:177], v[208:211], v[106:109]
	v_mfma_f32_16x16x32_bf16 v[110:113], v[166:169], v[208:211], v[110:113]
	v_mfma_f32_16x16x32_bf16 v[94:97], v[166:169], v[216:219], v[94:97]
	v_mfma_f32_16x16x32_bf16 v[90:93], v[174:177], v[216:219], v[90:93]
	v_mfma_f32_16x16x32_bf16 v[74:77], v[174:177], v[224:227], v[74:77]
	v_mfma_f32_16x16x32_bf16 v[78:81], v[166:169], v[224:227], v[78:81]
	v_mfma_f32_16x16x32_bf16 v[126:129], v[170:173], v[204:207], v[126:129]
	v_mfma_f32_16x16x32_bf16 v[122:125], v[180:183], v[204:207], v[122:125]
	v_mfma_f32_16x16x32_bf16 v[106:109], v[180:183], v[212:215], v[106:109]
	v_mfma_f32_16x16x32_bf16 v[110:113], v[170:173], v[212:215], v[110:113]
	v_mfma_f32_16x16x32_bf16 v[94:97], v[170:173], v[220:223], v[94:97]
	v_mfma_f32_16x16x32_bf16 v[90:93], v[180:183], v[220:223], v[90:93]
	v_mfma_f32_16x16x32_bf16 v[74:77], v[180:183], v[228:231], v[74:77]
	v_mfma_f32_16x16x32_bf16 v[78:81], v[170:173], v[228:231], v[78:81]
	v_mfma_f32_16x16x32_bf16 v[118:121], v[184:187], v[200:203], v[118:121]
	v_mfma_f32_16x16x32_bf16 v[114:117], v[192:195], v[200:203], v[114:117]
	v_mfma_f32_16x16x32_bf16 v[98:101], v[192:195], v[208:211], v[98:101]
	v_mfma_f32_16x16x32_bf16 v[102:105], v[184:187], v[208:211], v[102:105]
	v_mfma_f32_16x16x32_bf16 v[86:89], v[184:187], v[216:219], v[86:89]
	v_mfma_f32_16x16x32_bf16 v[82:85], v[192:195], v[216:219], v[82:85]
	v_mfma_f32_16x16x32_bf16 v[66:69], v[192:195], v[224:227], v[66:69]
	v_mfma_f32_16x16x32_bf16 v[70:73], v[184:187], v[224:227], v[70:73]
	v_mfma_f32_16x16x32_bf16 v[118:121], v[188:191], v[204:207], v[118:121]
	v_mfma_f32_16x16x32_bf16 v[114:117], v[196:199], v[204:207], v[114:117]
	v_mfma_f32_16x16x32_bf16 v[98:101], v[196:199], v[212:215], v[98:101]
	v_mfma_f32_16x16x32_bf16 v[102:105], v[188:191], v[212:215], v[102:105]
	v_mfma_f32_16x16x32_bf16 v[86:89], v[188:191], v[220:223], v[86:89]
	v_mfma_f32_16x16x32_bf16 v[82:85], v[196:199], v[220:223], v[82:85]
	v_mfma_f32_16x16x32_bf16 v[66:69], v[196:199], v[228:231], v[66:69]
	v_mfma_f32_16x16x32_bf16 v[70:73], v[188:191], v[228:231], v[70:73]
	s_barrier
	s_setprio 0
	s_add_i32 s34, s51, s17
	v_lshl_add_u64 v[160:161], v[160:161], 0, s[6:7]
	s_mov_b32 m0, s34
	ds_read_b128 v[200:203], v164 offset:49152
	ds_read_b128 v[204:207], v164 offset:50176
	ds_read_b128 v[208:211], v164 offset:51200
	ds_read_b128 v[212:215], v164 offset:52224
	ds_read_b128 v[216:219], v164 offset:53248
	ds_read_b128 v[220:223], v164 offset:54272
	ds_read_b128 v[224:227], v164 offset:55296
	ds_read_b128 v[228:231], v164 offset:56320
	global_load_lds_dwordx4 v[160:161], off
	s_add_i32 m0, s34, 0x2000
	s_add_u32 s30, s30, 0x80080
	v_lshl_add_u64 v[160:161], v[232:233], 0, s[6:7]
	s_addc_u32 s31, s31, 0
	s_add_i32 s34, s56, s17
	global_load_lds_dwordx4 v[160:161], off
	v_lshl_add_u64 v[160:161], s[30:31], 0, v[138:139]
	s_mov_b32 m0, s34
	s_nop 0
	global_load_lds_dwordx4 v[160:161], off
	v_lshl_add_u64 v[160:161], s[30:31], 0, v[142:143]
	s_add_i32 m0, s34, 0x2000
	s_nop 0
	global_load_lds_dwordx4 v[160:161], off
	v_lshl_add_u64 v[160:161], v[234:235], 0, s[6:7]
	s_mov_b32 m0, s40
	s_nop 0
	global_load_lds_dwordx4 v[160:161], off
	v_lshl_add_u64 v[160:161], v[236:237], 0, s[6:7]
	s_mov_b32 m0, s41
	s_nop 0
	global_load_lds_dwordx4 v[160:161], off
	s_waitcnt vmcnt(8)
	s_waitcnt lgkmcnt(0)
	s_setprio 1
	s_barrier
	v_mfma_f32_16x16x32_bf16 v[62:65], v[166:169], v[200:203], v[62:65]
	v_mfma_f32_16x16x32_bf16 v[58:61], v[174:177], v[200:203], v[58:61]
	v_mfma_f32_16x16x32_bf16 v[42:45], v[174:177], v[208:211], v[42:45]
	v_mfma_f32_16x16x32_bf16 v[46:49], v[166:169], v[208:211], v[46:49]
	v_mfma_f32_16x16x32_bf16 v[30:33], v[166:169], v[216:219], v[30:33]
	v_mfma_f32_16x16x32_bf16 v[26:29], v[174:177], v[216:219], v[26:29]
	v_mfma_f32_16x16x32_bf16 v[10:13], v[174:177], v[224:227], v[10:13]
	v_mfma_f32_16x16x32_bf16 v[14:17], v[166:169], v[224:227], v[14:17]
	v_mfma_f32_16x16x32_bf16 v[62:65], v[170:173], v[204:207], v[62:65]
	v_mfma_f32_16x16x32_bf16 v[58:61], v[180:183], v[204:207], v[58:61]
	v_mfma_f32_16x16x32_bf16 v[42:45], v[180:183], v[212:215], v[42:45]
	v_mfma_f32_16x16x32_bf16 v[46:49], v[170:173], v[212:215], v[46:49]
	v_mfma_f32_16x16x32_bf16 v[30:33], v[170:173], v[220:223], v[30:33]
	v_mfma_f32_16x16x32_bf16 v[26:29], v[180:183], v[220:223], v[26:29]
	v_mfma_f32_16x16x32_bf16 v[10:13], v[180:183], v[228:231], v[10:13]
	v_mfma_f32_16x16x32_bf16 v[14:17], v[170:173], v[228:231], v[14:17]
	v_mfma_f32_16x16x32_bf16 v[54:57], v[184:187], v[200:203], v[54:57]
	v_mfma_f32_16x16x32_bf16 v[50:53], v[192:195], v[200:203], v[50:53]
	v_mfma_f32_16x16x32_bf16 v[34:37], v[192:195], v[208:211], v[34:37]
	v_mfma_f32_16x16x32_bf16 v[38:41], v[184:187], v[208:211], v[38:41]
	v_mfma_f32_16x16x32_bf16 v[22:25], v[184:187], v[216:219], v[22:25]
	v_mfma_f32_16x16x32_bf16 v[18:21], v[192:195], v[216:219], v[18:21]
	v_mfma_f32_16x16x32_bf16 v[2:5], v[192:195], v[224:227], v[2:5]
	v_mfma_f32_16x16x32_bf16 v[6:9], v[184:187], v[224:227], v[6:9]
	v_mfma_f32_16x16x32_bf16 v[54:57], v[188:191], v[204:207], v[54:57]
	v_mfma_f32_16x16x32_bf16 v[50:53], v[196:199], v[204:207], v[50:53]
	v_mfma_f32_16x16x32_bf16 v[34:37], v[196:199], v[212:215], v[34:37]
	v_mfma_f32_16x16x32_bf16 v[38:41], v[188:191], v[212:215], v[38:41]
	v_mfma_f32_16x16x32_bf16 v[22:25], v[188:191], v[220:223], v[22:25]
	v_mfma_f32_16x16x32_bf16 v[18:21], v[196:199], v[220:223], v[18:21]
	v_mfma_f32_16x16x32_bf16 v[2:5], v[196:199], v[228:231], v[2:5]
	v_mfma_f32_16x16x32_bf16 v[6:9], v[188:191], v[228:231], v[6:9]
	s_barrier
	s_setprio 0
	s_add_i32 s50, s50, 2
	s_add_u32 s28, s28, 0x100
	s_addc_u32 s29, s29, 0
	s_add_u32 s48, s48, 0x100
	s_addc_u32 s49, s49, 0
	s_cmp_gt_u32 s50, 29
	s_cbranch_scc0 .LBB0_306
	s_and_b64 vcc, exec, s[8:9]
	s_cbranch_vccz .LBB0_314
	s_barrier
	v_lshl_add_u32 v160, s26, 8, v133
	s_cmp_gt_i32 s2, 35
	s_mov_b64 s[26:27], -1
	s_cbranch_scc1 .LBB0_315

.LBB0_986:
	ds_read_b128 v[148:151], v155
	ds_read_b128 v[158:161], v155 offset:1024
	ds_read_b128 v[162:165], v155 offset:2048
	ds_read_b128 v[166:169], v155 offset:3072
	ds_read_b128 v[170:173], v156
	ds_read_b128 v[174:177], v156 offset:1024
	ds_read_b128 v[180:183], v156 offset:2048
	ds_read_b128 v[184:187], v156 offset:3072
	s_add_u32 s26, s24, 0xfffc0080
	s_addc_u32 s27, s25, -1
	s_cmp_eq_u32 s49, 12
	s_cselect_b32 s29, s17, s27
	s_cselect_b32 s28, s45, s26
	s_cselect_b32 s27, s15, s48
	s_cselect_b32 s26, s46, s47
	v_lshl_add_u64 v[220:221], s[24:25], 0, v[138:139]
	s_add_i32 m0, s23, 0xc000
	ds_read_b128 v[188:191], v157
	ds_read_b128 v[192:195], v157 offset:1024
	ds_read_b128 v[196:199], v157 offset:2048
	ds_read_b128 v[200:203], v157 offset:3072
	ds_read_b128 v[204:207], v157 offset:4096
	ds_read_b128 v[208:211], v157 offset:5120
	ds_read_b128 v[212:215], v157 offset:6144
	ds_read_b128 v[216:219], v157 offset:7168
	global_load_lds_dwordx4 v[220:221], off
	v_lshl_add_u64 v[220:221], s[24:25], 0, v[140:141]
	s_add_i32 m0, s23, 0xe000
	s_nop 0
	global_load_lds_dwordx4 v[220:221], off
	s_waitcnt vmcnt(8)
	s_waitcnt lgkmcnt(0)
	s_setprio 1
	s_barrier
	v_mfma_f32_16x16x32_bf16 v[126:129], v[148:151], v[188:191], v[126:129]
	v_mfma_f32_16x16x32_bf16 v[122:125], v[162:165], v[188:191], v[122:125]
	v_mfma_f32_16x16x32_bf16 v[106:109], v[162:165], v[196:199], v[106:109]
	v_mfma_f32_16x16x32_bf16 v[110:113], v[148:151], v[196:199], v[110:113]
	v_mfma_f32_16x16x32_bf16 v[94:97], v[148:151], v[204:207], v[94:97]
	v_mfma_f32_16x16x32_bf16 v[90:93], v[162:165], v[204:207], v[90:93]
	v_mfma_f32_16x16x32_bf16 v[74:77], v[162:165], v[212:215], v[74:77]
	v_mfma_f32_16x16x32_bf16 v[78:81], v[148:151], v[212:215], v[78:81]
	v_mfma_f32_16x16x32_bf16 v[126:129], v[158:161], v[192:195], v[126:129]
	v_mfma_f32_16x16x32_bf16 v[122:125], v[166:169], v[192:195], v[122:125]
	v_mfma_f32_16x16x32_bf16 v[106:109], v[166:169], v[200:203], v[106:109]
	v_mfma_f32_16x16x32_bf16 v[110:113], v[158:161], v[200:203], v[110:113]
	v_mfma_f32_16x16x32_bf16 v[94:97], v[158:161], v[208:211], v[94:97]
	v_mfma_f32_16x16x32_bf16 v[90:93], v[166:169], v[208:211], v[90:93]
	v_mfma_f32_16x16x32_bf16 v[74:77], v[166:169], v[216:219], v[74:77]
	v_mfma_f32_16x16x32_bf16 v[78:81], v[158:161], v[216:219], v[78:81]
	v_mfma_f32_16x16x32_bf16 v[118:121], v[170:173], v[188:191], v[118:121]
	v_mfma_f32_16x16x32_bf16 v[114:117], v[180:183], v[188:191], v[114:117]
	v_mfma_f32_16x16x32_bf16 v[98:101], v[180:183], v[196:199], v[98:101]
	v_mfma_f32_16x16x32_bf16 v[102:105], v[170:173], v[196:199], v[102:105]
	v_mfma_f32_16x16x32_bf16 v[86:89], v[170:173], v[204:207], v[86:89]
	v_mfma_f32_16x16x32_bf16 v[82:85], v[180:183], v[204:207], v[82:85]
	v_mfma_f32_16x16x32_bf16 v[66:69], v[180:183], v[212:215], v[66:69]
	v_mfma_f32_16x16x32_bf16 v[70:73], v[170:173], v[212:215], v[70:73]
	v_mfma_f32_16x16x32_bf16 v[118:121], v[174:177], v[192:195], v[118:121]
	v_mfma_f32_16x16x32_bf16 v[114:117], v[184:187], v[192:195], v[114:117]
	v_mfma_f32_16x16x32_bf16 v[98:101], v[184:187], v[200:203], v[98:101]
	v_mfma_f32_16x16x32_bf16 v[102:105], v[174:177], v[200:203], v[102:105]
	v_mfma_f32_16x16x32_bf16 v[86:89], v[174:177], v[208:211], v[86:89]
	v_mfma_f32_16x16x32_bf16 v[82:85], v[184:187], v[208:211], v[82:85]
	v_mfma_f32_16x16x32_bf16 v[66:69], v[184:187], v[216:219], v[66:69]
	v_mfma_f32_16x16x32_bf16 v[70:73], v[174:177], v[216:219], v[70:73]
	s_barrier
	s_setprio 0
	s_add_i32 s50, s42, s30
	v_lshl_add_u64 v[220:221], s[26:27], 0, v[134:135]
	s_mov_b32 m0, s50
	ds_read_b128 v[188:191], v157 offset:16384
	ds_read_b128 v[192:195], v157 offset:17408
	ds_read_b128 v[196:199], v157 offset:18432
	ds_read_b128 v[200:203], v157 offset:19456
	ds_read_b128 v[204:207], v157 offset:20480
	ds_read_b128 v[208:211], v157 offset:21504
	ds_read_b128 v[212:215], v157 offset:22528
	ds_read_b128 v[216:219], v157 offset:23552
	global_load_lds_dwordx4 v[220:221], off
	s_add_i32 m0, s50, 0x2000
	s_add_u32 s50, s26, 0x40000
	v_lshl_add_u64 v[222:223], s[26:27], 0, v[130:131]
	s_addc_u32 s51, s27, 0
	s_add_i32 s56, s43, s30
	global_load_lds_dwordx4 v[222:223], off
	v_lshl_add_u64 v[224:225], s[50:51], 0, v[134:135]
	s_mov_b32 m0, s56
	v_lshl_add_u64 v[226:227], s[28:29], 0, v[132:133]
	global_load_lds_dwordx4 v[224:225], off
	v_lshl_add_u64 v[224:225], s[50:51], 0, v[130:131]
	s_add_i32 m0, s56, 0x2000
	s_nop 0
	global_load_lds_dwordx4 v[224:225], off
	v_lshl_add_u64 v[224:225], s[28:29], 0, v[136:137]
	s_mov_b32 m0, s23
	s_nop 0
	global_load_lds_dwordx4 v[224:225], off
	s_mov_b32 m0, s34
	s_nop 0
	global_load_lds_dwordx4 v[226:227], off
	s_waitcnt vmcnt(8)
	s_waitcnt lgkmcnt(0)
	s_setprio 1
	s_barrier
	v_mfma_f32_16x16x32_bf16 v[62:65], v[148:151], v[188:191], v[62:65]
	v_mfma_f32_16x16x32_bf16 v[58:61], v[162:165], v[188:191], v[58:61]
	v_mfma_f32_16x16x32_bf16 v[42:45], v[162:165], v[196:199], v[42:45]
	v_mfma_f32_16x16x32_bf16 v[46:49], v[148:151], v[196:199], v[46:49]
	v_mfma_f32_16x16x32_bf16 v[30:33], v[148:151], v[204:207], v[30:33]
	v_mfma_f32_16x16x32_bf16 v[26:29], v[162:165], v[204:207], v[26:29]
	v_mfma_f32_16x16x32_bf16 v[10:13], v[162:165], v[212:215], v[10:13]
	v_mfma_f32_16x16x32_bf16 v[14:17], v[148:151], v[212:215], v[14:17]
	v_mfma_f32_16x16x32_bf16 v[62:65], v[158:161], v[192:195], v[62:65]
	v_mfma_f32_16x16x32_bf16 v[58:61], v[166:169], v[192:195], v[58:61]
	v_mfma_f32_16x16x32_bf16 v[42:45], v[166:169], v[200:203], v[42:45]
	v_mfma_f32_16x16x32_bf16 v[46:49], v[158:161], v[200:203], v[46:49]
	v_mfma_f32_16x16x32_bf16 v[30:33], v[158:161], v[208:211], v[30:33]
	v_mfma_f32_16x16x32_bf16 v[26:29], v[166:169], v[208:211], v[26:29]
	v_mfma_f32_16x16x32_bf16 v[10:13], v[166:169], v[216:219], v[10:13]
	v_mfma_f32_16x16x32_bf16 v[14:17], v[158:161], v[216:219], v[14:17]
	v_mfma_f32_16x16x32_bf16 v[54:57], v[170:173], v[188:191], v[54:57]
	v_mfma_f32_16x16x32_bf16 v[50:53], v[180:183], v[188:191], v[50:53]
	v_mfma_f32_16x16x32_bf16 v[34:37], v[180:183], v[196:199], v[34:37]
	v_mfma_f32_16x16x32_bf16 v[38:41], v[170:173], v[196:199], v[38:41]
	v_mfma_f32_16x16x32_bf16 v[22:25], v[170:173], v[204:207], v[22:25]
	v_mfma_f32_16x16x32_bf16 v[18:21], v[180:183], v[204:207], v[18:21]
	v_mfma_f32_16x16x32_bf16 v[2:5], v[180:183], v[212:215], v[2:5]
	v_mfma_f32_16x16x32_bf16 v[6:9], v[170:173], v[212:215], v[6:9]
	v_mfma_f32_16x16x32_bf16 v[54:57], v[174:177], v[192:195], v[54:57]
	v_mfma_f32_16x16x32_bf16 v[50:53], v[184:187], v[192:195], v[50:53]
	v_mfma_f32_16x16x32_bf16 v[34:37], v[184:187], v[200:203], v[34:37]
	v_mfma_f32_16x16x32_bf16 v[38:41], v[174:177], v[200:203], v[38:41]
	v_mfma_f32_16x16x32_bf16 v[22:25], v[174:177], v[208:211], v[22:25]
	v_mfma_f32_16x16x32_bf16 v[18:21], v[184:187], v[208:211], v[18:21]
	v_mfma_f32_16x16x32_bf16 v[2:5], v[184:187], v[216:219], v[2:5]
	v_mfma_f32_16x16x32_bf16 v[6:9], v[174:177], v[216:219], v[6:9]
	s_barrier
	s_setprio 0
	s_add_i32 s50, 0, 0x18000
	s_add_i32 s51, 0, 0x1c000
	v_add_u32_e32 v166, s50, v153
	v_add_u32_e32 v179, s51, v153
	ds_read_b128 v[148:151], v166
	ds_read_b128 v[158:161], v166 offset:1024
	ds_read_b128 v[162:165], v166 offset:2048
	ds_read_b128 v[166:169], v166 offset:3072
	ds_read_b128 v[170:173], v179
	ds_read_b128 v[174:177], v179 offset:1024
	ds_read_b128 v[180:183], v179 offset:2048
	ds_read_b128 v[184:187], v179 offset:3072
	s_add_u32 s28, s28, 0x40000
	s_addc_u32 s29, s29, 0
	s_mov_b32 m0, s35
	v_lshl_add_u64 v[228:229], s[28:29], 0, v[136:137]
	ds_read_b128 v[188:191], v157 offset:32768
	ds_read_b128 v[192:195], v157 offset:33792
	ds_read_b128 v[196:199], v157 offset:34816
	ds_read_b128 v[200:203], v157 offset:35840
	ds_read_b128 v[204:207], v157 offset:36864
	ds_read_b128 v[208:211], v157 offset:37888
	ds_read_b128 v[212:215], v157 offset:38912
	ds_read_b128 v[216:219], v157 offset:39936
	global_load_lds_dwordx4 v[228:229], off
	v_lshl_add_u64 v[228:229], s[28:29], 0, v[132:133]
	s_mov_b32 m0, s36
	s_nop 0
	global_load_lds_dwordx4 v[228:229], off
	s_waitcnt vmcnt(8)
	s_waitcnt lgkmcnt(0)
	s_setprio 1
	s_barrier
	v_mfma_f32_16x16x32_bf16 v[126:129], v[148:151], v[188:191], v[126:129]
	v_mfma_f32_16x16x32_bf16 v[122:125], v[162:165], v[188:191], v[122:125]
	v_mfma_f32_16x16x32_bf16 v[106:109], v[162:165], v[196:199], v[106:109]
	v_mfma_f32_16x16x32_bf16 v[110:113], v[148:151], v[196:199], v[110:113]
	v_mfma_f32_16x16x32_bf16 v[94:97], v[148:151], v[204:207], v[94:97]
	v_mfma_f32_16x16x32_bf16 v[90:93], v[162:165], v[204:207], v[90:93]
	v_mfma_f32_16x16x32_bf16 v[74:77], v[162:165], v[212:215], v[74:77]
	v_mfma_f32_16x16x32_bf16 v[78:81], v[148:151], v[212:215], v[78:81]
	v_mfma_f32_16x16x32_bf16 v[126:129], v[158:161], v[192:195], v[126:129]
	v_mfma_f32_16x16x32_bf16 v[122:125], v[166:169], v[192:195], v[122:125]
	v_mfma_f32_16x16x32_bf16 v[106:109], v[166:169], v[200:203], v[106:109]
	v_mfma_f32_16x16x32_bf16 v[110:113], v[158:161], v[200:203], v[110:113]
	v_mfma_f32_16x16x32_bf16 v[94:97], v[158:161], v[208:211], v[94:97]
	v_mfma_f32_16x16x32_bf16 v[90:93], v[166:169], v[208:211], v[90:93]
	v_mfma_f32_16x16x32_bf16 v[74:77], v[166:169], v[216:219], v[74:77]
	v_mfma_f32_16x16x32_bf16 v[78:81], v[158:161], v[216:219], v[78:81]
	v_mfma_f32_16x16x32_bf16 v[118:121], v[170:173], v[188:191], v[118:121]
	v_mfma_f32_16x16x32_bf16 v[114:117], v[180:183], v[188:191], v[114:117]
	v_mfma_f32_16x16x32_bf16 v[98:101], v[180:183], v[196:199], v[98:101]
	v_mfma_f32_16x16x32_bf16 v[102:105], v[170:173], v[196:199], v[102:105]
	v_mfma_f32_16x16x32_bf16 v[86:89], v[170:173], v[204:207], v[86:89]
	v_mfma_f32_16x16x32_bf16 v[82:85], v[180:183], v[204:207], v[82:85]
	v_mfma_f32_16x16x32_bf16 v[66:69], v[180:183], v[212:215], v[66:69]
	v_mfma_f32_16x16x32_bf16 v[70:73], v[170:173], v[212:215], v[70:73]
	v_mfma_f32_16x16x32_bf16 v[118:121], v[174:177], v[192:195], v[118:121]
	v_mfma_f32_16x16x32_bf16 v[114:117], v[184:187], v[192:195], v[114:117]
	v_mfma_f32_16x16x32_bf16 v[98:101], v[184:187], v[200:203], v[98:101]
	v_mfma_f32_16x16x32_bf16 v[102:105], v[174:177], v[200:203], v[102:105]
	v_mfma_f32_16x16x32_bf16 v[86:89], v[174:177], v[208:211], v[86:89]
	v_mfma_f32_16x16x32_bf16 v[82:85], v[184:187], v[208:211], v[82:85]
	v_mfma_f32_16x16x32_bf16 v[66:69], v[184:187], v[216:219], v[66:69]
	v_mfma_f32_16x16x32_bf16 v[70:73], v[174:177], v[216:219], v[70:73]
	s_barrier
	s_setprio 0
	s_add_i32 s28, s50, s30
	v_lshl_add_u64 v[220:221], v[220:221], 0, s[4:5]
	s_mov_b32 m0, s28
	ds_read_b128 v[188:191], v157 offset:49152
	ds_read_b128 v[192:195], v157 offset:50176
	ds_read_b128 v[196:199], v157 offset:51200
	ds_read_b128 v[200:203], v157 offset:52224
	ds_read_b128 v[204:207], v157 offset:53248
	ds_read_b128 v[208:211], v157 offset:54272
	ds_read_b128 v[212:215], v157 offset:55296
	ds_read_b128 v[216:219], v157 offset:56320
	global_load_lds_dwordx4 v[220:221], off
	s_add_i32 m0, s28, 0x2000
	s_add_u32 s26, s26, 0x40080
	v_lshl_add_u64 v[220:221], v[222:223], 0, s[4:5]
	s_addc_u32 s27, s27, 0
	s_add_i32 s28, s51, s30
	global_load_lds_dwordx4 v[220:221], off
	v_lshl_add_u64 v[220:221], s[26:27], 0, v[134:135]
	s_mov_b32 m0, s28
	s_nop 0
	global_load_lds_dwordx4 v[220:221], off
	v_lshl_add_u64 v[220:221], s[26:27], 0, v[130:131]
	s_add_i32 m0, s28, 0x2000
	s_nop 0
	global_load_lds_dwordx4 v[220:221], off
	v_lshl_add_u64 v[220:221], v[224:225], 0, s[4:5]
	s_mov_b32 m0, s38
	s_nop 0
	global_load_lds_dwordx4 v[220:221], off
	v_lshl_add_u64 v[220:221], v[226:227], 0, s[4:5]
	s_mov_b32 m0, s39
	s_nop 0
	global_load_lds_dwordx4 v[220:221], off
	s_waitcnt vmcnt(8)
	s_waitcnt lgkmcnt(0)
	s_setprio 1
	s_barrier
	v_mfma_f32_16x16x32_bf16 v[62:65], v[148:151], v[188:191], v[62:65]
	v_mfma_f32_16x16x32_bf16 v[58:61], v[162:165], v[188:191], v[58:61]
	v_mfma_f32_16x16x32_bf16 v[42:45], v[162:165], v[196:199], v[42:45]
	v_mfma_f32_16x16x32_bf16 v[46:49], v[148:151], v[196:199], v[46:49]
	v_mfma_f32_16x16x32_bf16 v[30:33], v[148:151], v[204:207], v[30:33]
	v_mfma_f32_16x16x32_bf16 v[26:29], v[162:165], v[204:207], v[26:29]
	v_mfma_f32_16x16x32_bf16 v[10:13], v[162:165], v[212:215], v[10:13]
	v_mfma_f32_16x16x32_bf16 v[14:17], v[148:151], v[212:215], v[14:17]
	v_mfma_f32_16x16x32_bf16 v[62:65], v[158:161], v[192:195], v[62:65]
	v_mfma_f32_16x16x32_bf16 v[58:61], v[166:169], v[192:195], v[58:61]
	v_mfma_f32_16x16x32_bf16 v[42:45], v[166:169], v[200:203], v[42:45]
	v_mfma_f32_16x16x32_bf16 v[46:49], v[158:161], v[200:203], v[46:49]
	v_mfma_f32_16x16x32_bf16 v[30:33], v[158:161], v[208:211], v[30:33]
	v_mfma_f32_16x16x32_bf16 v[26:29], v[166:169], v[208:211], v[26:29]
	v_mfma_f32_16x16x32_bf16 v[10:13], v[166:169], v[216:219], v[10:13]
	v_mfma_f32_16x16x32_bf16 v[14:17], v[158:161], v[216:219], v[14:17]
	v_mfma_f32_16x16x32_bf16 v[54:57], v[170:173], v[188:191], v[54:57]
	v_mfma_f32_16x16x32_bf16 v[50:53], v[180:183], v[188:191], v[50:53]
	v_mfma_f32_16x16x32_bf16 v[34:37], v[180:183], v[196:199], v[34:37]
	v_mfma_f32_16x16x32_bf16 v[38:41], v[170:173], v[196:199], v[38:41]
	v_mfma_f32_16x16x32_bf16 v[22:25], v[170:173], v[204:207], v[22:25]
	v_mfma_f32_16x16x32_bf16 v[18:21], v[180:183], v[204:207], v[18:21]
	v_mfma_f32_16x16x32_bf16 v[2:5], v[180:183], v[212:215], v[2:5]
	v_mfma_f32_16x16x32_bf16 v[6:9], v[170:173], v[212:215], v[6:9]
	v_mfma_f32_16x16x32_bf16 v[54:57], v[174:177], v[192:195], v[54:57]
	v_mfma_f32_16x16x32_bf16 v[50:53], v[184:187], v[192:195], v[50:53]
	v_mfma_f32_16x16x32_bf16 v[34:37], v[184:187], v[200:203], v[34:37]
	v_mfma_f32_16x16x32_bf16 v[38:41], v[174:177], v[200:203], v[38:41]
	v_mfma_f32_16x16x32_bf16 v[22:25], v[174:177], v[208:211], v[22:25]
	v_mfma_f32_16x16x32_bf16 v[18:21], v[184:187], v[208:211], v[18:21]
	v_mfma_f32_16x16x32_bf16 v[2:5], v[184:187], v[216:219], v[2:5]
	v_mfma_f32_16x16x32_bf16 v[6:9], v[174:177], v[216:219], v[6:9]
	s_barrier
	s_setprio 0
	s_add_i32 s49, s49, 2
	s_add_u32 s24, s24, 0x100
	s_addc_u32 s25, s25, 0
	s_add_u32 s47, s47, 0x100
	s_addc_u32 s48, s48, 0
	s_cmp_gt_u32 s49, 13
	s_cbranch_scc0 .LBB0_986
	s_and_b64 vcc, exec, s[8:9]
	s_cbranch_vccz .LBB0_989
	s_barrier

.LBB0_1054:
	ds_read_b128 v[148:151], v155
	ds_read_b128 v[158:161], v155 offset:1024
	ds_read_b128 v[162:165], v155 offset:2048
	ds_read_b128 v[166:169], v155 offset:3072
	ds_read_b128 v[170:173], v156
	ds_read_b128 v[174:177], v156 offset:1024
	ds_read_b128 v[180:183], v156 offset:2048
	ds_read_b128 v[184:187], v156 offset:3072
	s_add_u32 s26, s24, 0xfffc0080
	s_addc_u32 s27, s25, -1
	s_cmp_eq_u32 s50, 12
	s_cselect_b32 s29, s17, s27
	s_cselect_b32 s28, s46, s26
	s_cselect_b32 s27, s15, s49
	s_cselect_b32 s26, s47, s48
	v_lshl_add_u64 v[220:221], s[24:25], 0, v[138:139]
	s_add_i32 m0, s23, 0xc000
	ds_read_b128 v[188:191], v157
	ds_read_b128 v[192:195], v157 offset:1024
	ds_read_b128 v[196:199], v157 offset:2048
	ds_read_b128 v[200:203], v157 offset:3072
	ds_read_b128 v[204:207], v157 offset:4096
	ds_read_b128 v[208:211], v157 offset:5120
	ds_read_b128 v[212:215], v157 offset:6144
	ds_read_b128 v[216:219], v157 offset:7168
	global_load_lds_dwordx4 v[220:221], off
	v_lshl_add_u64 v[220:221], s[24:25], 0, v[140:141]
	s_add_i32 m0, s23, 0xe000
	s_nop 0
	global_load_lds_dwordx4 v[220:221], off
	s_waitcnt vmcnt(8)
	s_waitcnt lgkmcnt(0)
	s_setprio 1
	s_barrier
	v_mfma_f32_16x16x32_bf16 v[118:121], v[148:151], v[188:191], v[118:121]
	v_mfma_f32_16x16x32_bf16 v[114:117], v[162:165], v[188:191], v[114:117]
	v_mfma_f32_16x16x32_bf16 v[98:101], v[162:165], v[196:199], v[98:101]
	v_mfma_f32_16x16x32_bf16 v[102:105], v[148:151], v[196:199], v[102:105]
	v_mfma_f32_16x16x32_bf16 v[86:89], v[148:151], v[204:207], v[86:89]
	v_mfma_f32_16x16x32_bf16 v[82:85], v[162:165], v[204:207], v[82:85]
	v_mfma_f32_16x16x32_bf16 v[66:69], v[162:165], v[212:215], v[66:69]
	v_mfma_f32_16x16x32_bf16 v[70:73], v[148:151], v[212:215], v[70:73]
	v_mfma_f32_16x16x32_bf16 v[118:121], v[158:161], v[192:195], v[118:121]
	v_mfma_f32_16x16x32_bf16 v[114:117], v[166:169], v[192:195], v[114:117]
	v_mfma_f32_16x16x32_bf16 v[98:101], v[166:169], v[200:203], v[98:101]
	v_mfma_f32_16x16x32_bf16 v[102:105], v[158:161], v[200:203], v[102:105]
	v_mfma_f32_16x16x32_bf16 v[86:89], v[158:161], v[208:211], v[86:89]
	v_mfma_f32_16x16x32_bf16 v[82:85], v[166:169], v[208:211], v[82:85]
	v_mfma_f32_16x16x32_bf16 v[66:69], v[166:169], v[216:219], v[66:69]
	v_mfma_f32_16x16x32_bf16 v[70:73], v[158:161], v[216:219], v[70:73]
	v_mfma_f32_16x16x32_bf16 v[126:129], v[170:173], v[188:191], v[126:129]
	v_mfma_f32_16x16x32_bf16 v[122:125], v[180:183], v[188:191], v[122:125]
	v_mfma_f32_16x16x32_bf16 v[106:109], v[180:183], v[196:199], v[106:109]
	v_mfma_f32_16x16x32_bf16 v[110:113], v[170:173], v[196:199], v[110:113]
	v_mfma_f32_16x16x32_bf16 v[94:97], v[170:173], v[204:207], v[94:97]
	v_mfma_f32_16x16x32_bf16 v[90:93], v[180:183], v[204:207], v[90:93]
	v_mfma_f32_16x16x32_bf16 v[74:77], v[180:183], v[212:215], v[74:77]
	v_mfma_f32_16x16x32_bf16 v[78:81], v[170:173], v[212:215], v[78:81]
	v_mfma_f32_16x16x32_bf16 v[126:129], v[174:177], v[192:195], v[126:129]
	v_mfma_f32_16x16x32_bf16 v[122:125], v[184:187], v[192:195], v[122:125]
	v_mfma_f32_16x16x32_bf16 v[106:109], v[184:187], v[200:203], v[106:109]
	v_mfma_f32_16x16x32_bf16 v[110:113], v[174:177], v[200:203], v[110:113]
	v_mfma_f32_16x16x32_bf16 v[94:97], v[174:177], v[208:211], v[94:97]
	v_mfma_f32_16x16x32_bf16 v[90:93], v[184:187], v[208:211], v[90:93]
	v_mfma_f32_16x16x32_bf16 v[74:77], v[184:187], v[216:219], v[74:77]
	v_mfma_f32_16x16x32_bf16 v[78:81], v[174:177], v[216:219], v[78:81]
	s_barrier
	s_setprio 0
	s_add_i32 s51, s42, s30
	v_lshl_add_u64 v[220:221], s[26:27], 0, v[134:135]
	s_mov_b32 m0, s51
	ds_read_b128 v[188:191], v157 offset:16384
	ds_read_b128 v[192:195], v157 offset:17408
	ds_read_b128 v[196:199], v157 offset:18432
	ds_read_b128 v[200:203], v157 offset:19456
	ds_read_b128 v[204:207], v157 offset:20480
	ds_read_b128 v[208:211], v157 offset:21504
	ds_read_b128 v[212:215], v157 offset:22528
	ds_read_b128 v[216:219], v157 offset:23552
	global_load_lds_dwordx4 v[220:221], off
	s_add_i32 m0, s51, 0x2000
	s_add_u32 s56, s26, 0x40000
	v_lshl_add_u64 v[222:223], s[26:27], 0, v[130:131]
	s_addc_u32 s57, s27, 0
	s_add_i32 s51, s43, s30
	global_load_lds_dwordx4 v[222:223], off
	v_lshl_add_u64 v[224:225], s[56:57], 0, v[134:135]
	s_mov_b32 m0, s51
	v_lshl_add_u64 v[226:227], s[28:29], 0, v[132:133]
	global_load_lds_dwordx4 v[224:225], off
	v_lshl_add_u64 v[224:225], s[56:57], 0, v[130:131]
	s_add_i32 m0, s51, 0x2000
	s_nop 0
	global_load_lds_dwordx4 v[224:225], off
	v_lshl_add_u64 v[224:225], s[28:29], 0, v[136:137]
	s_mov_b32 m0, s23
	s_nop 0
	global_load_lds_dwordx4 v[224:225], off
	s_mov_b32 m0, s34
	s_nop 0
	global_load_lds_dwordx4 v[226:227], off
	s_waitcnt vmcnt(8)
	s_waitcnt lgkmcnt(0)
	s_setprio 1
	s_barrier
	v_mfma_f32_16x16x32_bf16 v[54:57], v[148:151], v[188:191], v[54:57]
	v_mfma_f32_16x16x32_bf16 v[50:53], v[162:165], v[188:191], v[50:53]
	v_mfma_f32_16x16x32_bf16 v[34:37], v[162:165], v[196:199], v[34:37]
	v_mfma_f32_16x16x32_bf16 v[38:41], v[148:151], v[196:199], v[38:41]
	v_mfma_f32_16x16x32_bf16 v[22:25], v[148:151], v[204:207], v[22:25]
	v_mfma_f32_16x16x32_bf16 v[18:21], v[162:165], v[204:207], v[18:21]
	v_mfma_f32_16x16x32_bf16 v[2:5], v[162:165], v[212:215], v[2:5]
	v_mfma_f32_16x16x32_bf16 v[6:9], v[148:151], v[212:215], v[6:9]
	v_mfma_f32_16x16x32_bf16 v[54:57], v[158:161], v[192:195], v[54:57]
	v_mfma_f32_16x16x32_bf16 v[50:53], v[166:169], v[192:195], v[50:53]
	v_mfma_f32_16x16x32_bf16 v[34:37], v[166:169], v[200:203], v[34:37]
	v_mfma_f32_16x16x32_bf16 v[38:41], v[158:161], v[200:203], v[38:41]
	v_mfma_f32_16x16x32_bf16 v[22:25], v[158:161], v[208:211], v[22:25]
	v_mfma_f32_16x16x32_bf16 v[18:21], v[166:169], v[208:211], v[18:21]
	v_mfma_f32_16x16x32_bf16 v[2:5], v[166:169], v[216:219], v[2:5]
	v_mfma_f32_16x16x32_bf16 v[6:9], v[158:161], v[216:219], v[6:9]
	v_mfma_f32_16x16x32_bf16 v[62:65], v[170:173], v[188:191], v[62:65]
	v_mfma_f32_16x16x32_bf16 v[58:61], v[180:183], v[188:191], v[58:61]
	v_mfma_f32_16x16x32_bf16 v[42:45], v[180:183], v[196:199], v[42:45]
	v_mfma_f32_16x16x32_bf16 v[46:49], v[170:173], v[196:199], v[46:49]
	v_mfma_f32_16x16x32_bf16 v[30:33], v[170:173], v[204:207], v[30:33]
	v_mfma_f32_16x16x32_bf16 v[26:29], v[180:183], v[204:207], v[26:29]
	v_mfma_f32_16x16x32_bf16 v[10:13], v[180:183], v[212:215], v[10:13]
	v_mfma_f32_16x16x32_bf16 v[14:17], v[170:173], v[212:215], v[14:17]
	v_mfma_f32_16x16x32_bf16 v[62:65], v[174:177], v[192:195], v[62:65]
	v_mfma_f32_16x16x32_bf16 v[58:61], v[184:187], v[192:195], v[58:61]
	v_mfma_f32_16x16x32_bf16 v[42:45], v[184:187], v[200:203], v[42:45]
	v_mfma_f32_16x16x32_bf16 v[46:49], v[174:177], v[200:203], v[46:49]
	v_mfma_f32_16x16x32_bf16 v[30:33], v[174:177], v[208:211], v[30:33]
	v_mfma_f32_16x16x32_bf16 v[26:29], v[184:187], v[208:211], v[26:29]
	v_mfma_f32_16x16x32_bf16 v[10:13], v[184:187], v[216:219], v[10:13]
	v_mfma_f32_16x16x32_bf16 v[14:17], v[174:177], v[216:219], v[14:17]
	s_barrier
	s_setprio 0
	s_add_i32 s51, 0, 0x18000
	s_add_i32 s56, 0, 0x1c000
	v_add_u32_e32 v166, s51, v153
	v_add_u32_e32 v179, s56, v153
	ds_read_b128 v[148:151], v166
	ds_read_b128 v[158:161], v166 offset:1024
	ds_read_b128 v[162:165], v166 offset:2048
	ds_read_b128 v[166:169], v166 offset:3072
	ds_read_b128 v[170:173], v179
	ds_read_b128 v[174:177], v179 offset:1024
	ds_read_b128 v[180:183], v179 offset:2048
	ds_read_b128 v[184:187], v179 offset:3072
	s_add_u32 s28, s28, 0x40000
	s_addc_u32 s29, s29, 0
	s_mov_b32 m0, s35
	v_lshl_add_u64 v[228:229], s[28:29], 0, v[136:137]
	ds_read_b128 v[188:191], v157 offset:32768
	ds_read_b128 v[192:195], v157 offset:33792
	ds_read_b128 v[196:199], v157 offset:34816
	ds_read_b128 v[200:203], v157 offset:35840
	ds_read_b128 v[204:207], v157 offset:36864
	ds_read_b128 v[208:211], v157 offset:37888
	ds_read_b128 v[212:215], v157 offset:38912
	ds_read_b128 v[216:219], v157 offset:39936
	global_load_lds_dwordx4 v[228:229], off
	v_lshl_add_u64 v[228:229], s[28:29], 0, v[132:133]
	s_mov_b32 m0, s36
	s_nop 0
	global_load_lds_dwordx4 v[228:229], off
	s_waitcnt vmcnt(8)
	s_waitcnt lgkmcnt(0)
	s_setprio 1
	s_barrier
	v_mfma_f32_16x16x32_bf16 v[118:121], v[148:151], v[188:191], v[118:121]
	v_mfma_f32_16x16x32_bf16 v[114:117], v[162:165], v[188:191], v[114:117]
	v_mfma_f32_16x16x32_bf16 v[98:101], v[162:165], v[196:199], v[98:101]
	v_mfma_f32_16x16x32_bf16 v[102:105], v[148:151], v[196:199], v[102:105]
	v_mfma_f32_16x16x32_bf16 v[86:89], v[148:151], v[204:207], v[86:89]
	v_mfma_f32_16x16x32_bf16 v[82:85], v[162:165], v[204:207], v[82:85]
	v_mfma_f32_16x16x32_bf16 v[66:69], v[162:165], v[212:215], v[66:69]
	v_mfma_f32_16x16x32_bf16 v[70:73], v[148:151], v[212:215], v[70:73]
	v_mfma_f32_16x16x32_bf16 v[118:121], v[158:161], v[192:195], v[118:121]
	v_mfma_f32_16x16x32_bf16 v[114:117], v[166:169], v[192:195], v[114:117]
	v_mfma_f32_16x16x32_bf16 v[98:101], v[166:169], v[200:203], v[98:101]
	v_mfma_f32_16x16x32_bf16 v[102:105], v[158:161], v[200:203], v[102:105]
	v_mfma_f32_16x16x32_bf16 v[86:89], v[158:161], v[208:211], v[86:89]
	v_mfma_f32_16x16x32_bf16 v[82:85], v[166:169], v[208:211], v[82:85]
	v_mfma_f32_16x16x32_bf16 v[66:69], v[166:169], v[216:219], v[66:69]
	v_mfma_f32_16x16x32_bf16 v[70:73], v[158:161], v[216:219], v[70:73]
	v_mfma_f32_16x16x32_bf16 v[126:129], v[170:173], v[188:191], v[126:129]
	v_mfma_f32_16x16x32_bf16 v[122:125], v[180:183], v[188:191], v[122:125]
	v_mfma_f32_16x16x32_bf16 v[106:109], v[180:183], v[196:199], v[106:109]
	v_mfma_f32_16x16x32_bf16 v[110:113], v[170:173], v[196:199], v[110:113]
	v_mfma_f32_16x16x32_bf16 v[94:97], v[170:173], v[204:207], v[94:97]
	v_mfma_f32_16x16x32_bf16 v[90:93], v[180:183], v[204:207], v[90:93]
	v_mfma_f32_16x16x32_bf16 v[74:77], v[180:183], v[212:215], v[74:77]
	v_mfma_f32_16x16x32_bf16 v[78:81], v[170:173], v[212:215], v[78:81]
	v_mfma_f32_16x16x32_bf16 v[126:129], v[174:177], v[192:195], v[126:129]
	v_mfma_f32_16x16x32_bf16 v[122:125], v[184:187], v[192:195], v[122:125]
	v_mfma_f32_16x16x32_bf16 v[106:109], v[184:187], v[200:203], v[106:109]
	v_mfma_f32_16x16x32_bf16 v[110:113], v[174:177], v[200:203], v[110:113]
	v_mfma_f32_16x16x32_bf16 v[94:97], v[174:177], v[208:211], v[94:97]
	v_mfma_f32_16x16x32_bf16 v[90:93], v[184:187], v[208:211], v[90:93]
	v_mfma_f32_16x16x32_bf16 v[74:77], v[184:187], v[216:219], v[74:77]
	v_mfma_f32_16x16x32_bf16 v[78:81], v[174:177], v[216:219], v[78:81]
	s_barrier
	s_setprio 0
	s_add_i32 s28, s51, s30
	v_lshl_add_u64 v[220:221], v[220:221], 0, s[2:3]
	s_mov_b32 m0, s28
	ds_read_b128 v[188:191], v157 offset:49152
	ds_read_b128 v[192:195], v157 offset:50176
	ds_read_b128 v[196:199], v157 offset:51200
	ds_read_b128 v[200:203], v157 offset:52224
	ds_read_b128 v[204:207], v157 offset:53248
	ds_read_b128 v[208:211], v157 offset:54272
	ds_read_b128 v[212:215], v157 offset:55296
	ds_read_b128 v[216:219], v157 offset:56320
	global_load_lds_dwordx4 v[220:221], off
	s_add_i32 m0, s28, 0x2000
	s_add_u32 s26, s26, 0x40080
	v_lshl_add_u64 v[220:221], v[222:223], 0, s[2:3]
	s_addc_u32 s27, s27, 0
	s_add_i32 s28, s56, s30
	global_load_lds_dwordx4 v[220:221], off
	v_lshl_add_u64 v[220:221], s[26:27], 0, v[134:135]
	s_mov_b32 m0, s28
	s_nop 0
	global_load_lds_dwordx4 v[220:221], off
	v_lshl_add_u64 v[220:221], s[26:27], 0, v[130:131]
	s_add_i32 m0, s28, 0x2000
	s_nop 0
	global_load_lds_dwordx4 v[220:221], off
	v_lshl_add_u64 v[220:221], v[224:225], 0, s[2:3]
	s_mov_b32 m0, s38
	s_nop 0
	global_load_lds_dwordx4 v[220:221], off
	v_lshl_add_u64 v[220:221], v[226:227], 0, s[2:3]
	s_mov_b32 m0, s39
	s_nop 0
	global_load_lds_dwordx4 v[220:221], off
	s_waitcnt vmcnt(8)
	s_waitcnt lgkmcnt(0)
	s_setprio 1
	s_barrier
	v_mfma_f32_16x16x32_bf16 v[54:57], v[148:151], v[188:191], v[54:57]
	v_mfma_f32_16x16x32_bf16 v[50:53], v[162:165], v[188:191], v[50:53]
	v_mfma_f32_16x16x32_bf16 v[34:37], v[162:165], v[196:199], v[34:37]
	v_mfma_f32_16x16x32_bf16 v[38:41], v[148:151], v[196:199], v[38:41]
	v_mfma_f32_16x16x32_bf16 v[22:25], v[148:151], v[204:207], v[22:25]
	v_mfma_f32_16x16x32_bf16 v[18:21], v[162:165], v[204:207], v[18:21]
	v_mfma_f32_16x16x32_bf16 v[2:5], v[162:165], v[212:215], v[2:5]
	v_mfma_f32_16x16x32_bf16 v[6:9], v[148:151], v[212:215], v[6:9]
	v_mfma_f32_16x16x32_bf16 v[54:57], v[158:161], v[192:195], v[54:57]
	v_mfma_f32_16x16x32_bf16 v[50:53], v[166:169], v[192:195], v[50:53]
	v_mfma_f32_16x16x32_bf16 v[34:37], v[166:169], v[200:203], v[34:37]
	v_mfma_f32_16x16x32_bf16 v[38:41], v[158:161], v[200:203], v[38:41]
	v_mfma_f32_16x16x32_bf16 v[22:25], v[158:161], v[208:211], v[22:25]
	v_mfma_f32_16x16x32_bf16 v[18:21], v[166:169], v[208:211], v[18:21]
	v_mfma_f32_16x16x32_bf16 v[2:5], v[166:169], v[216:219], v[2:5]
	v_mfma_f32_16x16x32_bf16 v[6:9], v[158:161], v[216:219], v[6:9]
	v_mfma_f32_16x16x32_bf16 v[62:65], v[170:173], v[188:191], v[62:65]
	v_mfma_f32_16x16x32_bf16 v[58:61], v[180:183], v[188:191], v[58:61]
	v_mfma_f32_16x16x32_bf16 v[42:45], v[180:183], v[196:199], v[42:45]
	v_mfma_f32_16x16x32_bf16 v[46:49], v[170:173], v[196:199], v[46:49]
	v_mfma_f32_16x16x32_bf16 v[30:33], v[170:173], v[204:207], v[30:33]
	v_mfma_f32_16x16x32_bf16 v[26:29], v[180:183], v[204:207], v[26:29]
	v_mfma_f32_16x16x32_bf16 v[10:13], v[180:183], v[212:215], v[10:13]
	v_mfma_f32_16x16x32_bf16 v[14:17], v[170:173], v[212:215], v[14:17]
	v_mfma_f32_16x16x32_bf16 v[62:65], v[174:177], v[192:195], v[62:65]
	v_mfma_f32_16x16x32_bf16 v[58:61], v[184:187], v[192:195], v[58:61]
	v_mfma_f32_16x16x32_bf16 v[42:45], v[184:187], v[200:203], v[42:45]
	v_mfma_f32_16x16x32_bf16 v[46:49], v[174:177], v[200:203], v[46:49]
	v_mfma_f32_16x16x32_bf16 v[30:33], v[174:177], v[208:211], v[30:33]
	v_mfma_f32_16x16x32_bf16 v[26:29], v[184:187], v[208:211], v[26:29]
	v_mfma_f32_16x16x32_bf16 v[10:13], v[184:187], v[216:219], v[10:13]
	v_mfma_f32_16x16x32_bf16 v[14:17], v[174:177], v[216:219], v[14:17]
	s_barrier
	s_setprio 0
	s_add_i32 s50, s50, 2
	s_add_u32 s24, s24, 0x100
	s_addc_u32 s25, s25, 0
	s_add_u32 s48, s48, 0x100
	s_addc_u32 s49, s49, 0
	s_cmp_gt_u32 s50, 13
	s_cbranch_scc0 .LBB0_1054
	s_and_b64 vcc, exec, s[8:9]
	s_cbranch_vccz .LBB0_1057
	s_barrier

.LBB0_1124:
	ds_read_b128 v[86:89], v182
	ds_read_b128 v[90:93], v182 offset:1024
	ds_read_b128 v[98:101], v182 offset:2048
	ds_read_b128 v[102:105], v182 offset:3072
	ds_read_b128 v[164:167], v183
	ds_read_b128 v[168:171], v183 offset:1024
	ds_read_b128 v[172:175], v183 offset:2048
	ds_read_b128 v[186:189], v183 offset:3072
	s_add_u32 s34, s30, 0xfff80080
	s_addc_u32 s35, s31, -1
	s_cmp_eq_u32 s59, 28
	s_cselect_b32 s37, s21, s35
	s_cselect_b32 s36, s27, s34
	s_cselect_b32 s35, s19, s58
	s_cselect_b32 s34, s29, s57
	v_lshl_add_u64 v[176:177], s[30:31], 0, v[156:157]
	s_add_i32 m0, s38, 0xc000
	ds_read_b128 v[190:193], v184
	ds_read_b128 v[194:197], v184 offset:1024
	ds_read_b128 v[198:201], v184 offset:2048
	ds_read_b128 v[202:205], v184 offset:3072
	ds_read_b128 v[206:209], v184 offset:4096
	ds_read_b128 v[210:213], v184 offset:5120
	ds_read_b128 v[214:217], v184 offset:6144
	ds_read_b128 v[218:221], v184 offset:7168
	global_load_lds_dwordx4 v[176:177], off
	v_lshl_add_u64 v[176:177], s[30:31], 0, v[158:159]
	s_add_i32 m0, s38, 0xe000
	s_nop 0
	global_load_lds_dwordx4 v[176:177], off
	s_waitcnt vmcnt(8)
	s_waitcnt lgkmcnt(0)
	s_setprio 1
	s_barrier
	v_mfma_f32_16x16x32_bf16 v[142:145], v[86:89], v[190:193], v[142:145]
	v_mfma_f32_16x16x32_bf16 v[138:141], v[98:101], v[190:193], v[138:141]
	v_mfma_f32_16x16x32_bf16 v[122:125], v[98:101], v[198:201], v[122:125]
	v_mfma_f32_16x16x32_bf16 v[126:129], v[86:89], v[198:201], v[126:129]
	v_mfma_f32_16x16x32_bf16 v[110:113], v[86:89], v[206:209], v[110:113]
	v_mfma_f32_16x16x32_bf16 v[106:109], v[98:101], v[206:209], v[106:109]
	v_mfma_f32_16x16x32_bf16 v[74:77], v[98:101], v[214:217], v[74:77]
	v_mfma_f32_16x16x32_bf16 v[78:81], v[86:89], v[214:217], v[78:81]
	v_mfma_f32_16x16x32_bf16 v[142:145], v[90:93], v[194:197], v[142:145]
	v_mfma_f32_16x16x32_bf16 v[138:141], v[102:105], v[194:197], v[138:141]
	v_mfma_f32_16x16x32_bf16 v[122:125], v[102:105], v[202:205], v[122:125]
	v_mfma_f32_16x16x32_bf16 v[126:129], v[90:93], v[202:205], v[126:129]
	v_mfma_f32_16x16x32_bf16 v[110:113], v[90:93], v[210:213], v[110:113]
	v_mfma_f32_16x16x32_bf16 v[106:109], v[102:105], v[210:213], v[106:109]
	v_mfma_f32_16x16x32_bf16 v[74:77], v[102:105], v[218:221], v[74:77]
	v_mfma_f32_16x16x32_bf16 v[78:81], v[90:93], v[218:221], v[78:81]
	v_mfma_f32_16x16x32_bf16 v[134:137], v[164:167], v[190:193], v[134:137]
	v_mfma_f32_16x16x32_bf16 v[130:133], v[172:175], v[190:193], v[130:133]
	v_mfma_f32_16x16x32_bf16 v[114:117], v[172:175], v[198:201], v[114:117]
	v_mfma_f32_16x16x32_bf16 v[118:121], v[164:167], v[198:201], v[118:121]
	v_mfma_f32_16x16x32_bf16 v[94:97], v[164:167], v[206:209], v[94:97]
	v_mfma_f32_16x16x32_bf16 v[82:85], v[172:175], v[206:209], v[82:85]
	v_mfma_f32_16x16x32_bf16 v[66:69], v[172:175], v[214:217], v[66:69]
	v_mfma_f32_16x16x32_bf16 v[70:73], v[164:167], v[214:217], v[70:73]
	v_mfma_f32_16x16x32_bf16 v[134:137], v[168:171], v[194:197], v[134:137]
	v_mfma_f32_16x16x32_bf16 v[130:133], v[186:189], v[194:197], v[130:133]
	v_mfma_f32_16x16x32_bf16 v[114:117], v[186:189], v[202:205], v[114:117]
	v_mfma_f32_16x16x32_bf16 v[118:121], v[168:171], v[202:205], v[118:121]
	v_mfma_f32_16x16x32_bf16 v[94:97], v[168:171], v[210:213], v[94:97]
	v_mfma_f32_16x16x32_bf16 v[82:85], v[186:189], v[210:213], v[82:85]
	v_mfma_f32_16x16x32_bf16 v[66:69], v[186:189], v[218:221], v[66:69]
	v_mfma_f32_16x16x32_bf16 v[70:73], v[168:171], v[218:221], v[70:73]
	s_barrier
	s_setprio 0
	s_add_i32 s68, s51, s33
	v_lshl_add_u64 v[176:177], s[34:35], 0, v[150:151]
	s_mov_b32 m0, s68
	ds_read_b128 v[190:193], v184 offset:16384
	ds_read_b128 v[194:197], v184 offset:17408
	ds_read_b128 v[198:201], v184 offset:18432
	ds_read_b128 v[202:205], v184 offset:19456
	ds_read_b128 v[206:209], v184 offset:20480
	ds_read_b128 v[210:213], v184 offset:21504
	ds_read_b128 v[214:217], v184 offset:22528
	ds_read_b128 v[218:221], v184 offset:23552
	global_load_lds_dwordx4 v[176:177], off
	s_add_i32 m0, s68, 0x2000
	s_add_u32 s68, s34, 0x80000
	v_lshl_add_u64 v[222:223], s[34:35], 0, v[154:155]
	s_addc_u32 s69, s35, 0
	s_add_i32 s70, s56, s33
	global_load_lds_dwordx4 v[222:223], off
	v_lshl_add_u64 v[224:225], s[68:69], 0, v[150:151]
	s_mov_b32 m0, s70
	v_lshl_add_u64 v[226:227], s[36:37], 0, v[152:153]
	global_load_lds_dwordx4 v[224:225], off
	v_lshl_add_u64 v[224:225], s[68:69], 0, v[154:155]
	s_add_i32 m0, s70, 0x2000
	s_nop 0
	global_load_lds_dwordx4 v[224:225], off
	v_lshl_add_u64 v[224:225], s[36:37], 0, v[148:149]
	s_mov_b32 m0, s38
	s_nop 0
	global_load_lds_dwordx4 v[224:225], off
	s_mov_b32 m0, s39
	s_nop 0
	global_load_lds_dwordx4 v[226:227], off
	s_waitcnt vmcnt(8)
	s_waitcnt lgkmcnt(0)
	s_setprio 1
	s_barrier
	v_mfma_f32_16x16x32_bf16 v[62:65], v[86:89], v[190:193], v[62:65]
	v_mfma_f32_16x16x32_bf16 v[58:61], v[98:101], v[190:193], v[58:61]
	v_mfma_f32_16x16x32_bf16 v[42:45], v[98:101], v[198:201], v[42:45]
	v_mfma_f32_16x16x32_bf16 v[46:49], v[86:89], v[198:201], v[46:49]
	v_mfma_f32_16x16x32_bf16 v[30:33], v[86:89], v[206:209], v[30:33]
	v_mfma_f32_16x16x32_bf16 v[26:29], v[98:101], v[206:209], v[26:29]
	v_mfma_f32_16x16x32_bf16 v[10:13], v[98:101], v[214:217], v[10:13]
	v_mfma_f32_16x16x32_bf16 v[14:17], v[86:89], v[214:217], v[14:17]
	v_mfma_f32_16x16x32_bf16 v[62:65], v[90:93], v[194:197], v[62:65]
	v_mfma_f32_16x16x32_bf16 v[58:61], v[102:105], v[194:197], v[58:61]
	v_mfma_f32_16x16x32_bf16 v[42:45], v[102:105], v[202:205], v[42:45]
	v_mfma_f32_16x16x32_bf16 v[46:49], v[90:93], v[202:205], v[46:49]
	v_mfma_f32_16x16x32_bf16 v[30:33], v[90:93], v[210:213], v[30:33]
	v_mfma_f32_16x16x32_bf16 v[26:29], v[102:105], v[210:213], v[26:29]
	v_mfma_f32_16x16x32_bf16 v[10:13], v[102:105], v[218:221], v[10:13]
	v_mfma_f32_16x16x32_bf16 v[14:17], v[90:93], v[218:221], v[14:17]
	v_mfma_f32_16x16x32_bf16 v[54:57], v[164:167], v[190:193], v[54:57]
	v_mfma_f32_16x16x32_bf16 v[50:53], v[172:175], v[190:193], v[50:53]
	v_mfma_f32_16x16x32_bf16 v[34:37], v[172:175], v[198:201], v[34:37]
	v_mfma_f32_16x16x32_bf16 v[38:41], v[164:167], v[198:201], v[38:41]
	v_mfma_f32_16x16x32_bf16 v[22:25], v[164:167], v[206:209], v[22:25]
	v_mfma_f32_16x16x32_bf16 v[18:21], v[172:175], v[206:209], v[18:21]
	v_mfma_f32_16x16x32_bf16 v[2:5], v[172:175], v[214:217], v[2:5]
	v_mfma_f32_16x16x32_bf16 v[6:9], v[164:167], v[214:217], v[6:9]
	v_mfma_f32_16x16x32_bf16 v[54:57], v[168:171], v[194:197], v[54:57]
	v_mfma_f32_16x16x32_bf16 v[50:53], v[186:189], v[194:197], v[50:53]
	v_mfma_f32_16x16x32_bf16 v[34:37], v[186:189], v[202:205], v[34:37]
	v_mfma_f32_16x16x32_bf16 v[38:41], v[168:171], v[202:205], v[38:41]
	v_mfma_f32_16x16x32_bf16 v[22:25], v[168:171], v[210:213], v[22:25]
	v_mfma_f32_16x16x32_bf16 v[18:21], v[186:189], v[210:213], v[18:21]
	v_mfma_f32_16x16x32_bf16 v[2:5], v[186:189], v[218:221], v[2:5]
	v_mfma_f32_16x16x32_bf16 v[6:9], v[168:171], v[218:221], v[6:9]
	s_barrier
	s_setprio 0
	s_add_i32 s68, 0, 0x18000
	s_add_i32 s69, 0, 0x1c000
	v_add_u32_e32 v102, s68, v180
	v_add_u32_e32 v185, s69, v180
	ds_read_b128 v[86:89], v102
	ds_read_b128 v[90:93], v102 offset:1024
	ds_read_b128 v[98:101], v102 offset:2048
	ds_read_b128 v[102:105], v102 offset:3072
	ds_read_b128 v[164:167], v185
	ds_read_b128 v[168:171], v185 offset:1024
	ds_read_b128 v[172:175], v185 offset:2048
	ds_read_b128 v[186:189], v185 offset:3072
	s_add_u32 s36, s36, 0x80000
	s_addc_u32 s37, s37, 0
	s_mov_b32 m0, s40
	v_lshl_add_u64 v[228:229], s[36:37], 0, v[148:149]
	ds_read_b128 v[190:193], v184 offset:32768
	ds_read_b128 v[194:197], v184 offset:33792
	ds_read_b128 v[198:201], v184 offset:34816
	ds_read_b128 v[202:205], v184 offset:35840
	ds_read_b128 v[206:209], v184 offset:36864
	ds_read_b128 v[210:213], v184 offset:37888
	ds_read_b128 v[214:217], v184 offset:38912
	ds_read_b128 v[218:221], v184 offset:39936
	global_load_lds_dwordx4 v[228:229], off
	v_lshl_add_u64 v[228:229], s[36:37], 0, v[152:153]
	s_mov_b32 m0, s41
	s_nop 0
	global_load_lds_dwordx4 v[228:229], off
	s_waitcnt vmcnt(8)
	s_waitcnt lgkmcnt(0)
	s_setprio 1
	s_barrier
	v_mfma_f32_16x16x32_bf16 v[142:145], v[86:89], v[190:193], v[142:145]
	v_mfma_f32_16x16x32_bf16 v[138:141], v[98:101], v[190:193], v[138:141]
	v_mfma_f32_16x16x32_bf16 v[122:125], v[98:101], v[198:201], v[122:125]
	v_mfma_f32_16x16x32_bf16 v[126:129], v[86:89], v[198:201], v[126:129]
	v_mfma_f32_16x16x32_bf16 v[110:113], v[86:89], v[206:209], v[110:113]
	v_mfma_f32_16x16x32_bf16 v[106:109], v[98:101], v[206:209], v[106:109]
	v_mfma_f32_16x16x32_bf16 v[74:77], v[98:101], v[214:217], v[74:77]
	v_mfma_f32_16x16x32_bf16 v[78:81], v[86:89], v[214:217], v[78:81]
	v_mfma_f32_16x16x32_bf16 v[142:145], v[90:93], v[194:197], v[142:145]
	v_mfma_f32_16x16x32_bf16 v[138:141], v[102:105], v[194:197], v[138:141]
	v_mfma_f32_16x16x32_bf16 v[122:125], v[102:105], v[202:205], v[122:125]
	v_mfma_f32_16x16x32_bf16 v[126:129], v[90:93], v[202:205], v[126:129]
	v_mfma_f32_16x16x32_bf16 v[110:113], v[90:93], v[210:213], v[110:113]
	v_mfma_f32_16x16x32_bf16 v[106:109], v[102:105], v[210:213], v[106:109]
	v_mfma_f32_16x16x32_bf16 v[74:77], v[102:105], v[218:221], v[74:77]
	v_mfma_f32_16x16x32_bf16 v[78:81], v[90:93], v[218:221], v[78:81]
	v_mfma_f32_16x16x32_bf16 v[134:137], v[164:167], v[190:193], v[134:137]
	v_mfma_f32_16x16x32_bf16 v[130:133], v[172:175], v[190:193], v[130:133]
	v_mfma_f32_16x16x32_bf16 v[114:117], v[172:175], v[198:201], v[114:117]
	v_mfma_f32_16x16x32_bf16 v[118:121], v[164:167], v[198:201], v[118:121]
	v_mfma_f32_16x16x32_bf16 v[94:97], v[164:167], v[206:209], v[94:97]
	v_mfma_f32_16x16x32_bf16 v[82:85], v[172:175], v[206:209], v[82:85]
	v_mfma_f32_16x16x32_bf16 v[66:69], v[172:175], v[214:217], v[66:69]
	v_mfma_f32_16x16x32_bf16 v[70:73], v[164:167], v[214:217], v[70:73]
	v_mfma_f32_16x16x32_bf16 v[134:137], v[168:171], v[194:197], v[134:137]
	v_mfma_f32_16x16x32_bf16 v[130:133], v[186:189], v[194:197], v[130:133]
	v_mfma_f32_16x16x32_bf16 v[114:117], v[186:189], v[202:205], v[114:117]
	v_mfma_f32_16x16x32_bf16 v[118:121], v[168:171], v[202:205], v[118:121]
	v_mfma_f32_16x16x32_bf16 v[94:97], v[168:171], v[210:213], v[94:97]
	v_mfma_f32_16x16x32_bf16 v[82:85], v[186:189], v[210:213], v[82:85]
	v_mfma_f32_16x16x32_bf16 v[66:69], v[186:189], v[218:221], v[66:69]
	v_mfma_f32_16x16x32_bf16 v[70:73], v[168:171], v[218:221], v[70:73]
	s_barrier
	s_setprio 0
	s_add_i32 s36, s68, s33
	v_lshl_add_u64 v[176:177], v[176:177], 0, s[2:3]
	s_mov_b32 m0, s36
	ds_read_b128 v[190:193], v184 offset:49152
	ds_read_b128 v[194:197], v184 offset:50176
	ds_read_b128 v[198:201], v184 offset:51200
	ds_read_b128 v[202:205], v184 offset:52224
	ds_read_b128 v[206:209], v184 offset:53248
	ds_read_b128 v[210:213], v184 offset:54272
	ds_read_b128 v[214:217], v184 offset:55296
	ds_read_b128 v[218:221], v184 offset:56320
	global_load_lds_dwordx4 v[176:177], off
	s_add_i32 m0, s36, 0x2000
	s_add_u32 s34, s34, 0x80080
	v_lshl_add_u64 v[176:177], v[222:223], 0, s[2:3]
	s_addc_u32 s35, s35, 0
	s_add_i32 s36, s69, s33
	global_load_lds_dwordx4 v[176:177], off
	v_lshl_add_u64 v[176:177], s[34:35], 0, v[150:151]
	s_mov_b32 m0, s36
	s_nop 0
	global_load_lds_dwordx4 v[176:177], off
	v_lshl_add_u64 v[176:177], s[34:35], 0, v[154:155]
	s_add_i32 m0, s36, 0x2000
	s_nop 0
	global_load_lds_dwordx4 v[176:177], off
	v_lshl_add_u64 v[176:177], v[224:225], 0, s[2:3]
	s_mov_b32 m0, s43
	s_nop 0
	global_load_lds_dwordx4 v[176:177], off
	v_lshl_add_u64 v[176:177], v[226:227], 0, s[2:3]
	s_mov_b32 m0, s44
	s_nop 0
	global_load_lds_dwordx4 v[176:177], off
	s_waitcnt vmcnt(8)
	s_waitcnt lgkmcnt(0)
	s_setprio 1
	s_barrier
	v_mfma_f32_16x16x32_bf16 v[62:65], v[86:89], v[190:193], v[62:65]
	v_mfma_f32_16x16x32_bf16 v[58:61], v[98:101], v[190:193], v[58:61]
	v_mfma_f32_16x16x32_bf16 v[42:45], v[98:101], v[198:201], v[42:45]
	v_mfma_f32_16x16x32_bf16 v[46:49], v[86:89], v[198:201], v[46:49]
	v_mfma_f32_16x16x32_bf16 v[30:33], v[86:89], v[206:209], v[30:33]
	v_mfma_f32_16x16x32_bf16 v[26:29], v[98:101], v[206:209], v[26:29]
	v_mfma_f32_16x16x32_bf16 v[10:13], v[98:101], v[214:217], v[10:13]
	v_mfma_f32_16x16x32_bf16 v[14:17], v[86:89], v[214:217], v[14:17]
	v_mfma_f32_16x16x32_bf16 v[62:65], v[90:93], v[194:197], v[62:65]
	v_mfma_f32_16x16x32_bf16 v[58:61], v[102:105], v[194:197], v[58:61]
	v_mfma_f32_16x16x32_bf16 v[42:45], v[102:105], v[202:205], v[42:45]
	v_mfma_f32_16x16x32_bf16 v[46:49], v[90:93], v[202:205], v[46:49]
	v_mfma_f32_16x16x32_bf16 v[30:33], v[90:93], v[210:213], v[30:33]
	v_mfma_f32_16x16x32_bf16 v[26:29], v[102:105], v[210:213], v[26:29]
	v_mfma_f32_16x16x32_bf16 v[10:13], v[102:105], v[218:221], v[10:13]
	v_mfma_f32_16x16x32_bf16 v[14:17], v[90:93], v[218:221], v[14:17]
	v_mfma_f32_16x16x32_bf16 v[54:57], v[164:167], v[190:193], v[54:57]
	v_mfma_f32_16x16x32_bf16 v[50:53], v[172:175], v[190:193], v[50:53]
	v_mfma_f32_16x16x32_bf16 v[34:37], v[172:175], v[198:201], v[34:37]
	v_mfma_f32_16x16x32_bf16 v[38:41], v[164:167], v[198:201], v[38:41]
	v_mfma_f32_16x16x32_bf16 v[22:25], v[164:167], v[206:209], v[22:25]
	v_mfma_f32_16x16x32_bf16 v[18:21], v[172:175], v[206:209], v[18:21]
	v_mfma_f32_16x16x32_bf16 v[2:5], v[172:175], v[214:217], v[2:5]
	v_mfma_f32_16x16x32_bf16 v[6:9], v[164:167], v[214:217], v[6:9]
	v_mfma_f32_16x16x32_bf16 v[54:57], v[168:171], v[194:197], v[54:57]
	v_mfma_f32_16x16x32_bf16 v[50:53], v[186:189], v[194:197], v[50:53]
	v_mfma_f32_16x16x32_bf16 v[34:37], v[186:189], v[202:205], v[34:37]
	v_mfma_f32_16x16x32_bf16 v[38:41], v[168:171], v[202:205], v[38:41]
	v_mfma_f32_16x16x32_bf16 v[22:25], v[168:171], v[210:213], v[22:25]
	v_mfma_f32_16x16x32_bf16 v[18:21], v[186:189], v[210:213], v[18:21]
	v_mfma_f32_16x16x32_bf16 v[2:5], v[186:189], v[218:221], v[2:5]
	v_mfma_f32_16x16x32_bf16 v[6:9], v[168:171], v[218:221], v[6:9]
	s_barrier
	s_setprio 0
	s_add_i32 s59, s59, 2
	s_add_u32 s30, s30, 0x100
	s_addc_u32 s31, s31, 0
	s_add_u32 s57, s57, 0x100
	s_addc_u32 s58, s58, 0
	s_cmp_gt_u32 s59, 29
	s_cbranch_scc0 .LBB0_1124
	s_and_b64 vcc, exec, s[16:17]
	s_cbranch_vccz .LBB0_1127
	s_barrier

.LBB0_1208:
	ds_read_b128 v[98:101], v175
	ds_read_b128 v[102:105], v175 offset:1024
	ds_read_b128 v[106:109], v175 offset:2048
	ds_read_b128 v[110:113], v175 offset:3072
	ds_read_b128 v[164:167], v176
	ds_read_b128 v[168:171], v176 offset:1024
	ds_read_b128 v[182:185], v176 offset:2048
	ds_read_b128 v[186:189], v176 offset:3072
	s_add_u32 s28, s26, 0xfff80080
	s_addc_u32 s29, s27, -1
	s_cmp_eq_u32 s58, 28
	s_cselect_b32 s31, s21, s29
	s_cselect_b32 s30, s50, s28
	s_cselect_b32 s29, s19, s57
	s_cselect_b32 s28, s51, s56
	v_lshl_add_u64 v[222:223], s[26:27], 0, v[156:157]
	s_add_i32 m0, s36, 0xc000
	ds_read_b128 v[190:193], v177
	ds_read_b128 v[194:197], v177 offset:1024
	ds_read_b128 v[198:201], v177 offset:2048
	ds_read_b128 v[202:205], v177 offset:3072
	ds_read_b128 v[206:209], v177 offset:4096
	ds_read_b128 v[210:213], v177 offset:5120
	ds_read_b128 v[214:217], v177 offset:6144
	ds_read_b128 v[218:221], v177 offset:7168
	global_load_lds_dwordx4 v[222:223], off
	v_lshl_add_u64 v[222:223], s[26:27], 0, v[158:159]
	s_add_i32 m0, s36, 0xe000
	s_nop 0
	global_load_lds_dwordx4 v[222:223], off
	s_waitcnt vmcnt(8)
	s_waitcnt lgkmcnt(0)
	s_setprio 1
	s_barrier
	v_mfma_f32_16x16x32_bf16 v[142:145], v[98:101], v[190:193], v[142:145]
	v_mfma_f32_16x16x32_bf16 v[138:141], v[106:109], v[190:193], v[138:141]
	v_mfma_f32_16x16x32_bf16 v[122:125], v[106:109], v[198:201], v[122:125]
	v_mfma_f32_16x16x32_bf16 v[126:129], v[98:101], v[198:201], v[126:129]
	v_mfma_f32_16x16x32_bf16 v[94:97], v[98:101], v[206:209], v[94:97]
	v_mfma_f32_16x16x32_bf16 v[90:93], v[106:109], v[206:209], v[90:93]
	v_mfma_f32_16x16x32_bf16 v[74:77], v[106:109], v[214:217], v[74:77]
	v_mfma_f32_16x16x32_bf16 v[78:81], v[98:101], v[214:217], v[78:81]
	v_mfma_f32_16x16x32_bf16 v[142:145], v[102:105], v[194:197], v[142:145]
	v_mfma_f32_16x16x32_bf16 v[138:141], v[110:113], v[194:197], v[138:141]
	v_mfma_f32_16x16x32_bf16 v[122:125], v[110:113], v[202:205], v[122:125]
	v_mfma_f32_16x16x32_bf16 v[126:129], v[102:105], v[202:205], v[126:129]
	v_mfma_f32_16x16x32_bf16 v[94:97], v[102:105], v[210:213], v[94:97]
	v_mfma_f32_16x16x32_bf16 v[90:93], v[110:113], v[210:213], v[90:93]
	v_mfma_f32_16x16x32_bf16 v[74:77], v[110:113], v[218:221], v[74:77]
	v_mfma_f32_16x16x32_bf16 v[78:81], v[102:105], v[218:221], v[78:81]
	v_mfma_f32_16x16x32_bf16 v[134:137], v[164:167], v[190:193], v[134:137]
	v_mfma_f32_16x16x32_bf16 v[130:133], v[182:185], v[190:193], v[130:133]
	v_mfma_f32_16x16x32_bf16 v[114:117], v[182:185], v[198:201], v[114:117]
	v_mfma_f32_16x16x32_bf16 v[118:121], v[164:167], v[198:201], v[118:121]
	v_mfma_f32_16x16x32_bf16 v[86:89], v[164:167], v[206:209], v[86:89]
	v_mfma_f32_16x16x32_bf16 v[82:85], v[182:185], v[206:209], v[82:85]
	v_mfma_f32_16x16x32_bf16 v[66:69], v[182:185], v[214:217], v[66:69]
	v_mfma_f32_16x16x32_bf16 v[70:73], v[164:167], v[214:217], v[70:73]
	v_mfma_f32_16x16x32_bf16 v[134:137], v[168:171], v[194:197], v[134:137]
	v_mfma_f32_16x16x32_bf16 v[130:133], v[186:189], v[194:197], v[130:133]
	v_mfma_f32_16x16x32_bf16 v[114:117], v[186:189], v[202:205], v[114:117]
	v_mfma_f32_16x16x32_bf16 v[118:121], v[168:171], v[202:205], v[118:121]
	v_mfma_f32_16x16x32_bf16 v[86:89], v[168:171], v[210:213], v[86:89]
	v_mfma_f32_16x16x32_bf16 v[82:85], v[186:189], v[210:213], v[82:85]
	v_mfma_f32_16x16x32_bf16 v[66:69], v[186:189], v[218:221], v[66:69]
	v_mfma_f32_16x16x32_bf16 v[70:73], v[168:171], v[218:221], v[70:73]
	s_barrier
	s_setprio 0
	s_add_i32 s59, s45, s33
	v_lshl_add_u64 v[222:223], s[28:29], 0, v[152:153]
	s_mov_b32 m0, s59
	ds_read_b128 v[190:193], v177 offset:16384
	ds_read_b128 v[194:197], v177 offset:17408
	ds_read_b128 v[198:201], v177 offset:18432
	ds_read_b128 v[202:205], v177 offset:19456
	ds_read_b128 v[206:209], v177 offset:20480
	ds_read_b128 v[210:213], v177 offset:21504
	ds_read_b128 v[214:217], v177 offset:22528
	ds_read_b128 v[218:221], v177 offset:23552
	global_load_lds_dwordx4 v[222:223], off
	s_add_i32 m0, s59, 0x2000
	s_add_u32 s68, s28, 0x80000
	v_lshl_add_u64 v[224:225], s[28:29], 0, v[148:149]
	s_addc_u32 s69, s29, 0
	s_add_i32 s59, s46, s33
	global_load_lds_dwordx4 v[224:225], off
	v_lshl_add_u64 v[226:227], s[68:69], 0, v[152:153]
	s_mov_b32 m0, s59
	v_lshl_add_u64 v[228:229], s[30:31], 0, v[150:151]
	global_load_lds_dwordx4 v[226:227], off
	v_lshl_add_u64 v[226:227], s[68:69], 0, v[148:149]
	s_add_i32 m0, s59, 0x2000
	s_nop 0
	global_load_lds_dwordx4 v[226:227], off
	v_lshl_add_u64 v[226:227], s[30:31], 0, v[154:155]
	s_mov_b32 m0, s36
	s_nop 0
	global_load_lds_dwordx4 v[226:227], off
	s_mov_b32 m0, s37
	s_nop 0
	global_load_lds_dwordx4 v[228:229], off
	s_waitcnt vmcnt(8)
	s_waitcnt lgkmcnt(0)
	s_setprio 1
	s_barrier
	v_mfma_f32_16x16x32_bf16 v[62:65], v[98:101], v[190:193], v[62:65]
	v_mfma_f32_16x16x32_bf16 v[58:61], v[106:109], v[190:193], v[58:61]
	v_mfma_f32_16x16x32_bf16 v[42:45], v[106:109], v[198:201], v[42:45]
	v_mfma_f32_16x16x32_bf16 v[46:49], v[98:101], v[198:201], v[46:49]
	v_mfma_f32_16x16x32_bf16 v[30:33], v[98:101], v[206:209], v[30:33]
	v_mfma_f32_16x16x32_bf16 v[26:29], v[106:109], v[206:209], v[26:29]
	v_mfma_f32_16x16x32_bf16 v[10:13], v[106:109], v[214:217], v[10:13]
	v_mfma_f32_16x16x32_bf16 v[14:17], v[98:101], v[214:217], v[14:17]
	v_mfma_f32_16x16x32_bf16 v[62:65], v[102:105], v[194:197], v[62:65]
	v_mfma_f32_16x16x32_bf16 v[58:61], v[110:113], v[194:197], v[58:61]
	v_mfma_f32_16x16x32_bf16 v[42:45], v[110:113], v[202:205], v[42:45]
	v_mfma_f32_16x16x32_bf16 v[46:49], v[102:105], v[202:205], v[46:49]
	v_mfma_f32_16x16x32_bf16 v[30:33], v[102:105], v[210:213], v[30:33]
	v_mfma_f32_16x16x32_bf16 v[26:29], v[110:113], v[210:213], v[26:29]
	v_mfma_f32_16x16x32_bf16 v[10:13], v[110:113], v[218:221], v[10:13]
	v_mfma_f32_16x16x32_bf16 v[14:17], v[102:105], v[218:221], v[14:17]
	v_mfma_f32_16x16x32_bf16 v[54:57], v[164:167], v[190:193], v[54:57]
	v_mfma_f32_16x16x32_bf16 v[50:53], v[182:185], v[190:193], v[50:53]
	v_mfma_f32_16x16x32_bf16 v[34:37], v[182:185], v[198:201], v[34:37]
	v_mfma_f32_16x16x32_bf16 v[38:41], v[164:167], v[198:201], v[38:41]
	v_mfma_f32_16x16x32_bf16 v[22:25], v[164:167], v[206:209], v[22:25]
	v_mfma_f32_16x16x32_bf16 v[18:21], v[182:185], v[206:209], v[18:21]
	v_mfma_f32_16x16x32_bf16 v[2:5], v[182:185], v[214:217], v[2:5]
	v_mfma_f32_16x16x32_bf16 v[6:9], v[164:167], v[214:217], v[6:9]
	v_mfma_f32_16x16x32_bf16 v[54:57], v[168:171], v[194:197], v[54:57]
	v_mfma_f32_16x16x32_bf16 v[50:53], v[186:189], v[194:197], v[50:53]
	v_mfma_f32_16x16x32_bf16 v[34:37], v[186:189], v[202:205], v[34:37]
	v_mfma_f32_16x16x32_bf16 v[38:41], v[168:171], v[202:205], v[38:41]
	v_mfma_f32_16x16x32_bf16 v[22:25], v[168:171], v[210:213], v[22:25]
	v_mfma_f32_16x16x32_bf16 v[18:21], v[186:189], v[210:213], v[18:21]
	v_mfma_f32_16x16x32_bf16 v[2:5], v[186:189], v[218:221], v[2:5]
	v_mfma_f32_16x16x32_bf16 v[6:9], v[168:171], v[218:221], v[6:9]
	s_barrier
	s_setprio 0
	s_add_i32 s59, 0, 0x18000
	s_add_i32 s68, 0, 0x1c000
	v_add_u32_e32 v110, s59, v173
	v_add_u32_e32 v181, s68, v173
	ds_read_b128 v[98:101], v110
	ds_read_b128 v[102:105], v110 offset:1024
	ds_read_b128 v[106:109], v110 offset:2048
	ds_read_b128 v[110:113], v110 offset:3072
	ds_read_b128 v[164:167], v181
	ds_read_b128 v[168:171], v181 offset:1024
	ds_read_b128 v[182:185], v181 offset:2048
	ds_read_b128 v[186:189], v181 offset:3072
	s_add_u32 s30, s30, 0x80000
	s_addc_u32 s31, s31, 0
	s_mov_b32 m0, s38
	v_lshl_add_u64 v[230:231], s[30:31], 0, v[154:155]
	ds_read_b128 v[190:193], v177 offset:32768
	ds_read_b128 v[194:197], v177 offset:33792
	ds_read_b128 v[198:201], v177 offset:34816
	ds_read_b128 v[202:205], v177 offset:35840
	ds_read_b128 v[206:209], v177 offset:36864
	ds_read_b128 v[210:213], v177 offset:37888
	ds_read_b128 v[214:217], v177 offset:38912
	ds_read_b128 v[218:221], v177 offset:39936
	global_load_lds_dwordx4 v[230:231], off
	v_lshl_add_u64 v[230:231], s[30:31], 0, v[150:151]
	s_mov_b32 m0, s39
	s_nop 0
	global_load_lds_dwordx4 v[230:231], off
	s_waitcnt vmcnt(8)
	s_waitcnt lgkmcnt(0)
	s_setprio 1
	s_barrier
	v_mfma_f32_16x16x32_bf16 v[142:145], v[98:101], v[190:193], v[142:145]
	v_mfma_f32_16x16x32_bf16 v[138:141], v[106:109], v[190:193], v[138:141]
	v_mfma_f32_16x16x32_bf16 v[122:125], v[106:109], v[198:201], v[122:125]
	v_mfma_f32_16x16x32_bf16 v[126:129], v[98:101], v[198:201], v[126:129]
	v_mfma_f32_16x16x32_bf16 v[94:97], v[98:101], v[206:209], v[94:97]
	v_mfma_f32_16x16x32_bf16 v[90:93], v[106:109], v[206:209], v[90:93]
	v_mfma_f32_16x16x32_bf16 v[74:77], v[106:109], v[214:217], v[74:77]
	v_mfma_f32_16x16x32_bf16 v[78:81], v[98:101], v[214:217], v[78:81]
	v_mfma_f32_16x16x32_bf16 v[142:145], v[102:105], v[194:197], v[142:145]
	v_mfma_f32_16x16x32_bf16 v[138:141], v[110:113], v[194:197], v[138:141]
	v_mfma_f32_16x16x32_bf16 v[122:125], v[110:113], v[202:205], v[122:125]
	v_mfma_f32_16x16x32_bf16 v[126:129], v[102:105], v[202:205], v[126:129]
	v_mfma_f32_16x16x32_bf16 v[94:97], v[102:105], v[210:213], v[94:97]
	v_mfma_f32_16x16x32_bf16 v[90:93], v[110:113], v[210:213], v[90:93]
	v_mfma_f32_16x16x32_bf16 v[74:77], v[110:113], v[218:221], v[74:77]
	v_mfma_f32_16x16x32_bf16 v[78:81], v[102:105], v[218:221], v[78:81]
	v_mfma_f32_16x16x32_bf16 v[134:137], v[164:167], v[190:193], v[134:137]
	v_mfma_f32_16x16x32_bf16 v[130:133], v[182:185], v[190:193], v[130:133]
	v_mfma_f32_16x16x32_bf16 v[114:117], v[182:185], v[198:201], v[114:117]
	v_mfma_f32_16x16x32_bf16 v[118:121], v[164:167], v[198:201], v[118:121]
	v_mfma_f32_16x16x32_bf16 v[86:89], v[164:167], v[206:209], v[86:89]
	v_mfma_f32_16x16x32_bf16 v[82:85], v[182:185], v[206:209], v[82:85]
	v_mfma_f32_16x16x32_bf16 v[66:69], v[182:185], v[214:217], v[66:69]
	v_mfma_f32_16x16x32_bf16 v[70:73], v[164:167], v[214:217], v[70:73]
	v_mfma_f32_16x16x32_bf16 v[134:137], v[168:171], v[194:197], v[134:137]
	v_mfma_f32_16x16x32_bf16 v[130:133], v[186:189], v[194:197], v[130:133]
	v_mfma_f32_16x16x32_bf16 v[114:117], v[186:189], v[202:205], v[114:117]
	v_mfma_f32_16x16x32_bf16 v[118:121], v[168:171], v[202:205], v[118:121]
	v_mfma_f32_16x16x32_bf16 v[86:89], v[168:171], v[210:213], v[86:89]
	v_mfma_f32_16x16x32_bf16 v[82:85], v[186:189], v[210:213], v[82:85]
	v_mfma_f32_16x16x32_bf16 v[66:69], v[186:189], v[218:221], v[66:69]
	v_mfma_f32_16x16x32_bf16 v[70:73], v[168:171], v[218:221], v[70:73]
	s_barrier
	s_setprio 0
	s_add_i32 s30, s59, s33
	v_lshl_add_u64 v[222:223], v[222:223], 0, s[8:9]
	s_mov_b32 m0, s30
	ds_read_b128 v[190:193], v177 offset:49152
	ds_read_b128 v[194:197], v177 offset:50176
	ds_read_b128 v[198:201], v177 offset:51200
	ds_read_b128 v[202:205], v177 offset:52224
	ds_read_b128 v[206:209], v177 offset:53248
	ds_read_b128 v[210:213], v177 offset:54272
	ds_read_b128 v[214:217], v177 offset:55296
	ds_read_b128 v[218:221], v177 offset:56320
	global_load_lds_dwordx4 v[222:223], off
	s_add_i32 m0, s30, 0x2000
	s_add_u32 s28, s28, 0x80080
	v_lshl_add_u64 v[222:223], v[224:225], 0, s[8:9]
	s_addc_u32 s29, s29, 0
	s_add_i32 s30, s68, s33
	global_load_lds_dwordx4 v[222:223], off
	v_lshl_add_u64 v[222:223], s[28:29], 0, v[152:153]
	s_mov_b32 m0, s30
	s_nop 0
	global_load_lds_dwordx4 v[222:223], off
	v_lshl_add_u64 v[222:223], s[28:29], 0, v[148:149]
	s_add_i32 m0, s30, 0x2000
	s_nop 0
	global_load_lds_dwordx4 v[222:223], off
	v_lshl_add_u64 v[222:223], v[226:227], 0, s[8:9]
	s_mov_b32 m0, s41
	s_nop 0
	global_load_lds_dwordx4 v[222:223], off
	v_lshl_add_u64 v[222:223], v[228:229], 0, s[8:9]
	s_mov_b32 m0, s42
	s_nop 0
	global_load_lds_dwordx4 v[222:223], off
	s_waitcnt vmcnt(8)
	s_waitcnt lgkmcnt(0)
	s_setprio 1
	s_barrier
	v_mfma_f32_16x16x32_bf16 v[62:65], v[98:101], v[190:193], v[62:65]
	v_mfma_f32_16x16x32_bf16 v[58:61], v[106:109], v[190:193], v[58:61]
	v_mfma_f32_16x16x32_bf16 v[42:45], v[106:109], v[198:201], v[42:45]
	v_mfma_f32_16x16x32_bf16 v[46:49], v[98:101], v[198:201], v[46:49]
	v_mfma_f32_16x16x32_bf16 v[30:33], v[98:101], v[206:209], v[30:33]
	v_mfma_f32_16x16x32_bf16 v[26:29], v[106:109], v[206:209], v[26:29]
	v_mfma_f32_16x16x32_bf16 v[10:13], v[106:109], v[214:217], v[10:13]
	v_mfma_f32_16x16x32_bf16 v[14:17], v[98:101], v[214:217], v[14:17]
	v_mfma_f32_16x16x32_bf16 v[62:65], v[102:105], v[194:197], v[62:65]
	v_mfma_f32_16x16x32_bf16 v[58:61], v[110:113], v[194:197], v[58:61]
	v_mfma_f32_16x16x32_bf16 v[42:45], v[110:113], v[202:205], v[42:45]
	v_mfma_f32_16x16x32_bf16 v[46:49], v[102:105], v[202:205], v[46:49]
	v_mfma_f32_16x16x32_bf16 v[30:33], v[102:105], v[210:213], v[30:33]
	v_mfma_f32_16x16x32_bf16 v[26:29], v[110:113], v[210:213], v[26:29]
	v_mfma_f32_16x16x32_bf16 v[10:13], v[110:113], v[218:221], v[10:13]
	v_mfma_f32_16x16x32_bf16 v[14:17], v[102:105], v[218:221], v[14:17]
	v_mfma_f32_16x16x32_bf16 v[54:57], v[164:167], v[190:193], v[54:57]
	v_mfma_f32_16x16x32_bf16 v[50:53], v[182:185], v[190:193], v[50:53]
	v_mfma_f32_16x16x32_bf16 v[34:37], v[182:185], v[198:201], v[34:37]
	v_mfma_f32_16x16x32_bf16 v[38:41], v[164:167], v[198:201], v[38:41]
	v_mfma_f32_16x16x32_bf16 v[22:25], v[164:167], v[206:209], v[22:25]
	v_mfma_f32_16x16x32_bf16 v[18:21], v[182:185], v[206:209], v[18:21]
	v_mfma_f32_16x16x32_bf16 v[2:5], v[182:185], v[214:217], v[2:5]
	v_mfma_f32_16x16x32_bf16 v[6:9], v[164:167], v[214:217], v[6:9]
	v_mfma_f32_16x16x32_bf16 v[54:57], v[168:171], v[194:197], v[54:57]
	v_mfma_f32_16x16x32_bf16 v[50:53], v[186:189], v[194:197], v[50:53]
	v_mfma_f32_16x16x32_bf16 v[34:37], v[186:189], v[202:205], v[34:37]
	v_mfma_f32_16x16x32_bf16 v[38:41], v[168:171], v[202:205], v[38:41]
	v_mfma_f32_16x16x32_bf16 v[22:25], v[168:171], v[210:213], v[22:25]
	v_mfma_f32_16x16x32_bf16 v[18:21], v[186:189], v[210:213], v[18:21]
	v_mfma_f32_16x16x32_bf16 v[2:5], v[186:189], v[218:221], v[2:5]
	v_mfma_f32_16x16x32_bf16 v[6:9], v[168:171], v[218:221], v[6:9]
	s_barrier
	s_setprio 0
	s_add_i32 s58, s58, 2
	s_add_u32 s26, s26, 0x100
	s_addc_u32 s27, s27, 0
	s_add_u32 s56, s56, 0x100
	s_addc_u32 s57, s57, 0
	s_cmp_gt_u32 s58, 29
	s_cbranch_scc0 .LBB0_1208
	s_and_b64 vcc, exec, s[16:17]
	s_cbranch_vccz .LBB0_1211
	s_barrier

.LBB0_1284:
	ds_read_b128 v[122:125], v173
	ds_read_b128 v[126:129], v173 offset:1024
	ds_read_b128 v[130:133], v173 offset:2048
	ds_read_b128 v[134:137], v173 offset:3072
	ds_read_b128 v[164:167], v174
	ds_read_b128 v[180:183], v174 offset:1024
	ds_read_b128 v[184:187], v174 offset:2048
	ds_read_b128 v[188:191], v174 offset:3072
	s_add_u32 s28, s26, 0x100
	s_addc_u32 s29, s27, 0
	s_cmpk_eq_i32 s60, 0x54
	s_cselect_b32 s35, s5, s29
	s_cselect_b32 s34, s4, s28
	s_cselect_b32 s31, s25, s59
	s_cselect_b32 s30, s24, s58
	v_lshl_add_u64 v[168:169], s[26:27], 0, v[156:157]
	s_add_i32 m0, s38, 0xc000
	ds_read_b128 v[192:195], v175
	ds_read_b128 v[196:199], v175 offset:1024
	ds_read_b128 v[200:203], v175 offset:2048
	ds_read_b128 v[204:207], v175 offset:3072
	ds_read_b128 v[208:211], v175 offset:4096
	ds_read_b128 v[212:215], v175 offset:5120
	ds_read_b128 v[216:219], v175 offset:6144
	ds_read_b128 v[220:223], v175 offset:7168
	global_load_lds_dwordx4 v[168:169], off
	v_lshl_add_u64 v[168:169], s[26:27], 0, v[158:159]
	s_add_i32 m0, s38, 0xe000
	s_nop 0
	global_load_lds_dwordx4 v[168:169], off
	s_waitcnt vmcnt(8)
	s_waitcnt lgkmcnt(0)
	s_setprio 1
	s_barrier
	v_mfma_f32_16x16x32_bf16 v[142:145], v[122:125], v[192:195], v[142:145]
	v_mfma_f32_16x16x32_bf16 v[138:141], v[130:133], v[192:195], v[138:141]
	v_mfma_f32_16x16x32_bf16 v[106:109], v[130:133], v[200:203], v[106:109]
	v_mfma_f32_16x16x32_bf16 v[110:113], v[122:125], v[200:203], v[110:113]
	v_mfma_f32_16x16x32_bf16 v[94:97], v[122:125], v[208:211], v[94:97]
	v_mfma_f32_16x16x32_bf16 v[90:93], v[130:133], v[208:211], v[90:93]
	v_mfma_f32_16x16x32_bf16 v[74:77], v[130:133], v[216:219], v[74:77]
	v_mfma_f32_16x16x32_bf16 v[78:81], v[122:125], v[216:219], v[78:81]
	v_mfma_f32_16x16x32_bf16 v[142:145], v[126:129], v[196:199], v[142:145]
	v_mfma_f32_16x16x32_bf16 v[138:141], v[134:137], v[196:199], v[138:141]
	v_mfma_f32_16x16x32_bf16 v[106:109], v[134:137], v[204:207], v[106:109]
	v_mfma_f32_16x16x32_bf16 v[110:113], v[126:129], v[204:207], v[110:113]
	v_mfma_f32_16x16x32_bf16 v[94:97], v[126:129], v[212:215], v[94:97]
	v_mfma_f32_16x16x32_bf16 v[90:93], v[134:137], v[212:215], v[90:93]
	v_mfma_f32_16x16x32_bf16 v[74:77], v[134:137], v[220:223], v[74:77]
	v_mfma_f32_16x16x32_bf16 v[78:81], v[126:129], v[220:223], v[78:81]
	v_mfma_f32_16x16x32_bf16 v[118:121], v[164:167], v[192:195], v[118:121]
	v_mfma_f32_16x16x32_bf16 v[114:117], v[184:187], v[192:195], v[114:117]
	v_mfma_f32_16x16x32_bf16 v[98:101], v[184:187], v[200:203], v[98:101]
	v_mfma_f32_16x16x32_bf16 v[102:105], v[164:167], v[200:203], v[102:105]
	v_mfma_f32_16x16x32_bf16 v[86:89], v[164:167], v[208:211], v[86:89]
	v_mfma_f32_16x16x32_bf16 v[82:85], v[184:187], v[208:211], v[82:85]
	v_mfma_f32_16x16x32_bf16 v[66:69], v[184:187], v[216:219], v[66:69]
	v_mfma_f32_16x16x32_bf16 v[70:73], v[164:167], v[216:219], v[70:73]
	v_mfma_f32_16x16x32_bf16 v[118:121], v[180:183], v[196:199], v[118:121]
	v_mfma_f32_16x16x32_bf16 v[114:117], v[188:191], v[196:199], v[114:117]
	v_mfma_f32_16x16x32_bf16 v[98:101], v[188:191], v[204:207], v[98:101]
	v_mfma_f32_16x16x32_bf16 v[102:105], v[180:183], v[204:207], v[102:105]
	v_mfma_f32_16x16x32_bf16 v[86:89], v[180:183], v[212:215], v[86:89]
	v_mfma_f32_16x16x32_bf16 v[82:85], v[188:191], v[212:215], v[82:85]
	v_mfma_f32_16x16x32_bf16 v[66:69], v[188:191], v[220:223], v[66:69]
	v_mfma_f32_16x16x32_bf16 v[70:73], v[180:183], v[220:223], v[70:73]
	s_barrier
	s_setprio 0
	s_add_i32 s26, s48, s33
	v_lshl_add_u64 v[168:169], s[30:31], 0, v[152:153]
	s_mov_b32 m0, s26
	ds_read_b128 v[192:195], v175 offset:16384
	ds_read_b128 v[196:199], v175 offset:17408
	ds_read_b128 v[200:203], v175 offset:18432
	ds_read_b128 v[204:207], v175 offset:19456
	ds_read_b128 v[208:211], v175 offset:20480
	ds_read_b128 v[212:215], v175 offset:21504
	ds_read_b128 v[216:219], v175 offset:22528
	ds_read_b128 v[220:223], v175 offset:23552
	global_load_lds_dwordx4 v[168:169], off
	s_add_i32 m0, s26, 0x2000
	s_add_u32 s26, s30, 0x160000
	v_lshl_add_u64 v[176:177], s[30:31], 0, v[148:149]
	s_addc_u32 s27, s31, 0
	s_add_i32 s61, s49, s33
	global_load_lds_dwordx4 v[176:177], off
	v_lshl_add_u64 v[224:225], s[26:27], 0, v[152:153]
	s_mov_b32 m0, s61
	v_lshl_add_u64 v[226:227], s[34:35], 0, v[150:151]
	global_load_lds_dwordx4 v[224:225], off
	v_lshl_add_u64 v[224:225], s[26:27], 0, v[148:149]
	s_add_i32 m0, s61, 0x2000
	s_nop 0
	global_load_lds_dwordx4 v[224:225], off
	v_lshl_add_u64 v[224:225], s[34:35], 0, v[154:155]
	s_mov_b32 m0, s38
	s_nop 0
	global_load_lds_dwordx4 v[224:225], off
	s_mov_b32 m0, s39
	s_nop 0
	global_load_lds_dwordx4 v[226:227], off
	s_waitcnt vmcnt(8)
	s_waitcnt lgkmcnt(0)
	s_setprio 1
	s_barrier
	v_mfma_f32_16x16x32_bf16 v[62:65], v[122:125], v[192:195], v[62:65]
	v_mfma_f32_16x16x32_bf16 v[58:61], v[130:133], v[192:195], v[58:61]
	v_mfma_f32_16x16x32_bf16 v[42:45], v[130:133], v[200:203], v[42:45]
	v_mfma_f32_16x16x32_bf16 v[46:49], v[122:125], v[200:203], v[46:49]
	v_mfma_f32_16x16x32_bf16 v[30:33], v[122:125], v[208:211], v[30:33]
	v_mfma_f32_16x16x32_bf16 v[26:29], v[130:133], v[208:211], v[26:29]
	v_mfma_f32_16x16x32_bf16 v[10:13], v[130:133], v[216:219], v[10:13]
	v_mfma_f32_16x16x32_bf16 v[14:17], v[122:125], v[216:219], v[14:17]
	v_mfma_f32_16x16x32_bf16 v[62:65], v[126:129], v[196:199], v[62:65]
	v_mfma_f32_16x16x32_bf16 v[58:61], v[134:137], v[196:199], v[58:61]
	v_mfma_f32_16x16x32_bf16 v[42:45], v[134:137], v[204:207], v[42:45]
	v_mfma_f32_16x16x32_bf16 v[46:49], v[126:129], v[204:207], v[46:49]
	v_mfma_f32_16x16x32_bf16 v[30:33], v[126:129], v[212:215], v[30:33]
	v_mfma_f32_16x16x32_bf16 v[26:29], v[134:137], v[212:215], v[26:29]
	v_mfma_f32_16x16x32_bf16 v[10:13], v[134:137], v[220:223], v[10:13]
	v_mfma_f32_16x16x32_bf16 v[14:17], v[126:129], v[220:223], v[14:17]
	v_mfma_f32_16x16x32_bf16 v[54:57], v[164:167], v[192:195], v[54:57]
	v_mfma_f32_16x16x32_bf16 v[50:53], v[184:187], v[192:195], v[50:53]
	v_mfma_f32_16x16x32_bf16 v[34:37], v[184:187], v[200:203], v[34:37]
	v_mfma_f32_16x16x32_bf16 v[38:41], v[164:167], v[200:203], v[38:41]
	v_mfma_f32_16x16x32_bf16 v[22:25], v[164:167], v[208:211], v[22:25]
	v_mfma_f32_16x16x32_bf16 v[18:21], v[184:187], v[208:211], v[18:21]
	v_mfma_f32_16x16x32_bf16 v[2:5], v[184:187], v[216:219], v[2:5]
	v_mfma_f32_16x16x32_bf16 v[6:9], v[164:167], v[216:219], v[6:9]
	v_mfma_f32_16x16x32_bf16 v[54:57], v[180:183], v[196:199], v[54:57]
	v_mfma_f32_16x16x32_bf16 v[50:53], v[188:191], v[196:199], v[50:53]
	v_mfma_f32_16x16x32_bf16 v[34:37], v[188:191], v[204:207], v[34:37]
	v_mfma_f32_16x16x32_bf16 v[38:41], v[180:183], v[204:207], v[38:41]
	v_mfma_f32_16x16x32_bf16 v[22:25], v[180:183], v[212:215], v[22:25]
	v_mfma_f32_16x16x32_bf16 v[18:21], v[188:191], v[212:215], v[18:21]
	v_mfma_f32_16x16x32_bf16 v[2:5], v[188:191], v[220:223], v[2:5]
	v_mfma_f32_16x16x32_bf16 v[6:9], v[180:183], v[220:223], v[6:9]
	s_barrier
	s_setprio 0
	s_add_i32 s61, 0, 0x18000
	s_add_i32 s68, 0, 0x1c000
	v_add_u32_e32 v134, s61, v171
	v_add_u32_e32 v179, s68, v171
	ds_read_b128 v[122:125], v134
	ds_read_b128 v[126:129], v134 offset:1024
	ds_read_b128 v[130:133], v134 offset:2048
	ds_read_b128 v[134:137], v134 offset:3072
	ds_read_b128 v[164:167], v179
	ds_read_b128 v[180:183], v179 offset:1024
	ds_read_b128 v[184:187], v179 offset:2048
	ds_read_b128 v[188:191], v179 offset:3072
	s_add_u32 s26, s34, 0x160000
	s_addc_u32 s27, s35, 0
	s_mov_b32 m0, s40
	v_lshl_add_u64 v[228:229], s[26:27], 0, v[154:155]
	ds_read_b128 v[192:195], v175 offset:32768
	ds_read_b128 v[196:199], v175 offset:33792
	ds_read_b128 v[200:203], v175 offset:34816
	ds_read_b128 v[204:207], v175 offset:35840
	ds_read_b128 v[208:211], v175 offset:36864
	ds_read_b128 v[212:215], v175 offset:37888
	ds_read_b128 v[216:219], v175 offset:38912
	ds_read_b128 v[220:223], v175 offset:39936
	global_load_lds_dwordx4 v[228:229], off
	v_lshl_add_u64 v[228:229], s[26:27], 0, v[150:151]
	s_mov_b32 m0, s41
	s_nop 0
	global_load_lds_dwordx4 v[228:229], off
	s_waitcnt vmcnt(8)
	s_waitcnt lgkmcnt(0)
	s_setprio 1
	s_barrier
	v_mfma_f32_16x16x32_bf16 v[142:145], v[122:125], v[192:195], v[142:145]
	v_mfma_f32_16x16x32_bf16 v[138:141], v[130:133], v[192:195], v[138:141]
	v_mfma_f32_16x16x32_bf16 v[106:109], v[130:133], v[200:203], v[106:109]
	v_mfma_f32_16x16x32_bf16 v[110:113], v[122:125], v[200:203], v[110:113]
	v_mfma_f32_16x16x32_bf16 v[94:97], v[122:125], v[208:211], v[94:97]
	v_mfma_f32_16x16x32_bf16 v[90:93], v[130:133], v[208:211], v[90:93]
	v_mfma_f32_16x16x32_bf16 v[74:77], v[130:133], v[216:219], v[74:77]
	v_mfma_f32_16x16x32_bf16 v[78:81], v[122:125], v[216:219], v[78:81]
	v_mfma_f32_16x16x32_bf16 v[142:145], v[126:129], v[196:199], v[142:145]
	v_mfma_f32_16x16x32_bf16 v[138:141], v[134:137], v[196:199], v[138:141]
	v_mfma_f32_16x16x32_bf16 v[106:109], v[134:137], v[204:207], v[106:109]
	v_mfma_f32_16x16x32_bf16 v[110:113], v[126:129], v[204:207], v[110:113]
	v_mfma_f32_16x16x32_bf16 v[94:97], v[126:129], v[212:215], v[94:97]
	v_mfma_f32_16x16x32_bf16 v[90:93], v[134:137], v[212:215], v[90:93]
	v_mfma_f32_16x16x32_bf16 v[74:77], v[134:137], v[220:223], v[74:77]
	v_mfma_f32_16x16x32_bf16 v[78:81], v[126:129], v[220:223], v[78:81]
	v_mfma_f32_16x16x32_bf16 v[118:121], v[164:167], v[192:195], v[118:121]
	v_mfma_f32_16x16x32_bf16 v[114:117], v[184:187], v[192:195], v[114:117]
	v_mfma_f32_16x16x32_bf16 v[98:101], v[184:187], v[200:203], v[98:101]
	v_mfma_f32_16x16x32_bf16 v[102:105], v[164:167], v[200:203], v[102:105]
	v_mfma_f32_16x16x32_bf16 v[86:89], v[164:167], v[208:211], v[86:89]
	v_mfma_f32_16x16x32_bf16 v[82:85], v[184:187], v[208:211], v[82:85]
	v_mfma_f32_16x16x32_bf16 v[66:69], v[184:187], v[216:219], v[66:69]
	v_mfma_f32_16x16x32_bf16 v[70:73], v[164:167], v[216:219], v[70:73]
	v_mfma_f32_16x16x32_bf16 v[118:121], v[180:183], v[196:199], v[118:121]
	v_mfma_f32_16x16x32_bf16 v[114:117], v[188:191], v[196:199], v[114:117]
	v_mfma_f32_16x16x32_bf16 v[98:101], v[188:191], v[204:207], v[98:101]
	v_mfma_f32_16x16x32_bf16 v[102:105], v[180:183], v[204:207], v[102:105]
	v_mfma_f32_16x16x32_bf16 v[86:89], v[180:183], v[212:215], v[86:89]
	v_mfma_f32_16x16x32_bf16 v[82:85], v[188:191], v[212:215], v[82:85]
	v_mfma_f32_16x16x32_bf16 v[66:69], v[188:191], v[220:223], v[66:69]
	v_mfma_f32_16x16x32_bf16 v[70:73], v[180:183], v[220:223], v[70:73]
	s_barrier
	s_setprio 0
	s_add_i32 s26, s61, s33
	v_lshl_add_u64 v[168:169], v[168:169], 0, s[8:9]
	s_mov_b32 m0, s26
	ds_read_b128 v[192:195], v175 offset:49152
	ds_read_b128 v[196:199], v175 offset:50176
	ds_read_b128 v[200:203], v175 offset:51200
	ds_read_b128 v[204:207], v175 offset:52224
	ds_read_b128 v[208:211], v175 offset:53248
	ds_read_b128 v[212:215], v175 offset:54272
	ds_read_b128 v[216:219], v175 offset:55296
	ds_read_b128 v[220:223], v175 offset:56320
	global_load_lds_dwordx4 v[168:169], off
	s_add_i32 m0, s26, 0x2000
	s_add_u32 s26, s30, 0x160080
	v_lshl_add_u64 v[168:169], v[176:177], 0, s[8:9]
	s_addc_u32 s27, s31, 0
	s_add_i32 s30, s68, s33
	global_load_lds_dwordx4 v[168:169], off
	v_lshl_add_u64 v[168:169], s[26:27], 0, v[152:153]
	s_mov_b32 m0, s30
	s_nop 0
	global_load_lds_dwordx4 v[168:169], off
	v_lshl_add_u64 v[168:169], s[26:27], 0, v[148:149]
	s_add_i32 m0, s30, 0x2000
	s_nop 0
	global_load_lds_dwordx4 v[168:169], off
	v_lshl_add_u64 v[168:169], v[224:225], 0, s[8:9]
	s_mov_b32 m0, s43
	s_nop 0
	global_load_lds_dwordx4 v[168:169], off
	v_lshl_add_u64 v[168:169], v[226:227], 0, s[8:9]
	s_mov_b32 m0, s44
	s_nop 0
	global_load_lds_dwordx4 v[168:169], off
	s_waitcnt vmcnt(8)
	s_waitcnt lgkmcnt(0)
	s_setprio 1
	s_barrier
	v_mfma_f32_16x16x32_bf16 v[62:65], v[122:125], v[192:195], v[62:65]
	v_mfma_f32_16x16x32_bf16 v[58:61], v[130:133], v[192:195], v[58:61]
	v_mfma_f32_16x16x32_bf16 v[42:45], v[130:133], v[200:203], v[42:45]
	v_mfma_f32_16x16x32_bf16 v[46:49], v[122:125], v[200:203], v[46:49]
	v_mfma_f32_16x16x32_bf16 v[30:33], v[122:125], v[208:211], v[30:33]
	v_mfma_f32_16x16x32_bf16 v[26:29], v[130:133], v[208:211], v[26:29]
	v_mfma_f32_16x16x32_bf16 v[10:13], v[130:133], v[216:219], v[10:13]
	v_mfma_f32_16x16x32_bf16 v[14:17], v[122:125], v[216:219], v[14:17]
	v_mfma_f32_16x16x32_bf16 v[62:65], v[126:129], v[196:199], v[62:65]
	v_mfma_f32_16x16x32_bf16 v[58:61], v[134:137], v[196:199], v[58:61]
	v_mfma_f32_16x16x32_bf16 v[42:45], v[134:137], v[204:207], v[42:45]
	v_mfma_f32_16x16x32_bf16 v[46:49], v[126:129], v[204:207], v[46:49]
	v_mfma_f32_16x16x32_bf16 v[30:33], v[126:129], v[212:215], v[30:33]
	v_mfma_f32_16x16x32_bf16 v[26:29], v[134:137], v[212:215], v[26:29]
	v_mfma_f32_16x16x32_bf16 v[10:13], v[134:137], v[220:223], v[10:13]
	v_mfma_f32_16x16x32_bf16 v[14:17], v[126:129], v[220:223], v[14:17]
	v_mfma_f32_16x16x32_bf16 v[54:57], v[164:167], v[192:195], v[54:57]
	v_mfma_f32_16x16x32_bf16 v[50:53], v[184:187], v[192:195], v[50:53]
	v_mfma_f32_16x16x32_bf16 v[34:37], v[184:187], v[200:203], v[34:37]
	v_mfma_f32_16x16x32_bf16 v[38:41], v[164:167], v[200:203], v[38:41]
	v_mfma_f32_16x16x32_bf16 v[22:25], v[164:167], v[208:211], v[22:25]
	v_mfma_f32_16x16x32_bf16 v[18:21], v[184:187], v[208:211], v[18:21]
	v_mfma_f32_16x16x32_bf16 v[2:5], v[184:187], v[216:219], v[2:5]
	v_mfma_f32_16x16x32_bf16 v[6:9], v[164:167], v[216:219], v[6:9]
	v_mfma_f32_16x16x32_bf16 v[54:57], v[180:183], v[196:199], v[54:57]
	v_mfma_f32_16x16x32_bf16 v[50:53], v[188:191], v[196:199], v[50:53]
	v_mfma_f32_16x16x32_bf16 v[34:37], v[188:191], v[204:207], v[34:37]
	v_mfma_f32_16x16x32_bf16 v[38:41], v[180:183], v[204:207], v[38:41]
	v_mfma_f32_16x16x32_bf16 v[22:25], v[180:183], v[212:215], v[22:25]
	v_mfma_f32_16x16x32_bf16 v[18:21], v[188:191], v[212:215], v[18:21]
	v_mfma_f32_16x16x32_bf16 v[2:5], v[188:191], v[220:223], v[2:5]
	v_mfma_f32_16x16x32_bf16 v[6:9], v[180:183], v[220:223], v[6:9]
	s_barrier
	s_setprio 0
	s_add_i32 s60, s60, 2
	s_add_u32 s58, s58, 0x100
	s_addc_u32 s59, s59, 0
	s_cmpk_gt_u32 s60, 0x55
	s_mov_b64 s[26:27], s[28:29]
	s_cbranch_scc0 .LBB0_1284
	s_and_b64 vcc, exec, s[12:13]
	s_cbranch_vccz .LBB0_1287
	s_barrier
